# non-temporal hint also on the w_ffn_in reads (phase 0 transposes and phase 1 bias GEMV) and the ctx row loads
# baseline (speedup 1.0000x reference)
.LBB0_60:
	s_andn2_b64 vcc, exec, s[6:7]
	s_cbranch_vccnz .LBB0_62
	s_lshl_b32 s6, s39, 6
	s_and_b32 s8, s6, 0x3c0
	s_lshl_b32 s6, s39, 2
	s_and_b32 s7, s6, 0x3fc0
	s_add_i32 s9, s7, 0xffffec00
	s_bfe_i32 s7, s39, 0x10005
	s_lshr_b32 s10, s9, 1
	v_mov_b32_e32 v12, v188
	s_and_b32 s7, s7, 0xb00
	s_and_b32 s10, s10, 0xf80
	s_and_b32 s6, s6, 64
	v_lshlrev_b32_e32 v0, 2, v12
	s_add_i32 s10, s10, s7
	v_ashrrev_i32_e32 v13, 4, v12
	v_and_b32_e32 v21, 60, v0
	s_or_b32 s6, s10, s6
	v_or_b32_e32 v4, s6, v21
	v_add_u32_e32 v5, s8, v13
	v_mov_b64_e32 v[0:1], s[84:85]
	v_mad_i64_i32 v[2:3], s[6:7], v5, s5, v[0:1]
	v_lshlrev_b32_e32 v10, 2, v4
	v_add_u32_e32 v4, 32, v5
	v_lshl_add_u64 v[2:3], v[2:3], 0, v[10:11]
	v_mad_i64_i32 v[0:1], s[6:7], v4, s5, v[0:1]
	v_lshl_add_u64 v[4:5], v[0:1], 0, v[10:11]
	global_load_dwordx4 v[0:3], v[2:3], off nt
	s_nop 0
	global_load_dwordx4 v[28:31], v[4:5], off nt
	v_lshlrev_b32_e32 v5, 3, v12
	v_ashrrev_i32_e32 v4, 3, v12
	v_and_b32_e32 v12, 56, v5
	v_mul_lo_u32 v10, v13, s4
	v_lshlrev_b32_e32 v13, 2, v4
	v_mul_u32_u24_e32 v22, 0x110, v12
	v_lshlrev_b32_e32 v21, 2, v21
	v_add3_u32 v13, 0, v22, v13
	v_add3_u32 v21, 0, v21, v10
	v_add_u32_e32 v22, 0x400, v13
	v_add_u32_e32 v4, s9, v4
	v_lshlrev_b32_e32 v10, 1, v12
	v_ashrrev_i32_e32 v5, 31, v4
	v_lshlrev_b64 v[4:5], 11, v[4:5]
	s_lshl_b32 s30, s8, 1
	v_lshl_add_u64 v[4:5], s[20:21], 0, v[4:5]
	v_lshl_add_u64 v[4:5], v[4:5], 0, s[30:31]
	v_lshl_add_u64 v[4:5], v[4:5], 0, v[10:11]
	s_waitcnt vmcnt(1)
	ds_write_b128 v21, v[0:3]
	s_waitcnt vmcnt(0)
	ds_write_b128 v21, v[28:31] offset:8704
	s_waitcnt lgkmcnt(0)
	s_barrier
	ds_read2_b32 v[0:1], v13 offset1:68
	ds_read2_b32 v[2:3], v13 offset0:136 offset1:204
	ds_read2_b32 v[12:13], v22 offset0:16 offset1:84
	ds_read2_b32 v[22:23], v22 offset0:152 offset1:220
	s_waitcnt lgkmcnt(3)
	v_cvt_pk_bf16_f32 v0, v0, v1
	s_waitcnt lgkmcnt(2)
	v_cvt_pk_bf16_f32 v1, v2, v3
	s_waitcnt lgkmcnt(1)
	v_cvt_pk_bf16_f32 v2, v12, v13
	s_waitcnt lgkmcnt(0)
	v_cvt_pk_bf16_f32 v3, v22, v23
	global_store_dwordx4 v[4:5], v[0:3], off
	s_barrier

.LBB0_135:
	s_cmp_lt_i32 s76, 2
	s_cselect_b64 s[0:1], -1, 0
	s_and_b64 s[4:5], s[0:1], s[2:3]
	s_andn2_b64 vcc, exec, s[4:5]
	s_cbranch_vccnz .LBB0_145
	v_and_b32_e32 v2, 63, v188
	v_lshlrev_b32_e32 v0, 4, v2
	v_lshlrev_b32_e32 v1, 3, v2
	v_readfirstlane_b32 s7, v188
	v_mov_b32_e32 v16, 0x3a800000
	v_mov_b32_e32 v17, 0x358637bd
	v_mov_b32_e32 v18, 1.0
	v_mov_b32_e32 v19, 1.0
	s_lshr_b32 s7, s7, 6
	s_lshl_b32 s6, s33, 3
	s_add_i32 s6, s6, s7
	s_add_u32 s12, s74, 0x5000
	s_addc_u32 s13, s75, 0
	s_cmpk_lt_u32 s6, 0x400
	s_cbranch_scc0 .Lp1_noctx0
	s_lshl_b32 s14, s6, 12
	s_add_u32 s14, s44, s14
	s_addc_u32 s15, s45, 0
	global_load_dwordx4 v[132:135], v0, s[14:15] nt
	global_load_dwordx4 v[136:139], v0, s[14:15] offset:1024 nt
	global_load_dwordx4 v[140:143], v0, s[14:15] offset:2048 nt
	global_load_dwordx4 v[144:147], v0, s[14:15] offset:3072 nt
.Lp1_noctx0:
	global_load_dwordx4 v[20:23], v0, s[52:53]
	global_load_dwordx4 v[24:27], v0, s[52:53] offset:1024
	global_load_dwordx4 v[28:31], v0, s[52:53] offset:2048
	global_load_dwordx4 v[32:35], v0, s[52:53] offset:3072
	s_add_u32 s14, s12, 0x0
	s_addc_u32 s15, s13, 0
	s_add_u32 s16, s14, 0x1000
	s_addc_u32 s17, s15, 0
	global_load_dwordx4 v[36:39], v0, s[14:15]
	global_load_dwordx4 v[40:43], v0, s[14:15] offset:1024
	global_load_dwordx4 v[44:47], v0, s[14:15] offset:2048
	global_load_dwordx4 v[48:51], v0, s[14:15] offset:3072
	global_load_dwordx4 v[52:55], v0, s[16:17]
	global_load_dwordx4 v[56:59], v0, s[16:17] offset:1024
	global_load_dwordx4 v[60:63], v0, s[16:17] offset:2048
	global_load_dwordx4 v[64:67], v0, s[16:17] offset:3072
	s_mov_b32 s16, s33
	s_cmpk_lt_u32 s16, 0xb0
	s_cbranch_scc0 .Lp1_nob0
	s_mul_i32 s17, s16, 0xba3
	s_lshr_b32 s17, s17, 16
	s_mul_i32 s18, s17, 22
	s_sub_i32 s18, s16, s18
	s_lshl_b32 s17, s17, 3
	s_add_i32 s17, s17, s7
	s_mul_i32 s19, s17, 0x58000
	s_add_u32 s22, s84, s19
	s_addc_u32 s23, s85, 0
	v_and_b32_e32 v3, 31, v2
	v_lshrrev_b32_e32 v8, 5, v2
	v_lshlrev_b32_e32 v3, 4, v3
	s_lshl_b32 s19, s18, 9
	v_mul_u32_u24_e32 v8, 0x2c00, v8
	v_add_u32_e32 v190, v8, v3
	v_add_u32_e32 v190, s19, v190
	global_load_dwordx4 v[148:151], v190, s[22:23] nt
	s_add_u32 s22, s22, 0x5800
	s_addc_u32 s23, s23, 0
	global_load_dwordx4 v[152:155], v190, s[22:23] nt
	s_add_u32 s22, s22, 0x5800
	s_addc_u32 s23, s23, 0
	global_load_dwordx4 v[156:159], v190, s[22:23] nt
	s_add_u32 s22, s22, 0x5800
	s_addc_u32 s23, s23, 0
	global_load_dwordx4 v[160:163], v190, s[22:23] nt
	s_add_u32 s22, s22, 0x5800
	s_addc_u32 s23, s23, 0
	global_load_dwordx4 v[164:167], v190, s[22:23] nt
	s_add_u32 s22, s22, 0x5800
	s_addc_u32 s23, s23, 0
	global_load_dwordx4 v[168:171], v190, s[22:23] nt
	s_add_u32 s22, s22, 0x5800
	s_addc_u32 s23, s23, 0
	global_load_dwordx4 v[172:175], v190, s[22:23] nt
	s_add_u32 s22, s22, 0x5800
	s_addc_u32 s23, s23, 0
	global_load_dwordx4 v[176:179], v190, s[22:23] nt
	s_add_u32 s22, s22, 0x5800
	s_addc_u32 s23, s23, 0
	global_load_dwordx4 v[180:183], v190, s[22:23] nt
	s_add_u32 s22, s22, 0x5800
	s_addc_u32 s23, s23, 0
	global_load_dwordx4 v[184:187], v190, s[22:23] nt
	s_add_u32 s22, s22, 0x5800
	s_addc_u32 s23, s23, 0
	global_load_dwordx4 v[192:195], v190, s[22:23] nt
	s_add_u32 s22, s22, 0x5800
	s_addc_u32 s23, s23, 0
	global_load_dwordx4 v[196:199], v190, s[22:23] nt
	s_add_u32 s22, s22, 0x5800
	s_addc_u32 s23, s23, 0
	global_load_dwordx4 v[200:203], v190, s[22:23] nt
	s_add_u32 s22, s22, 0x5800
	s_addc_u32 s23, s23, 0
	global_load_dwordx4 v[204:207], v190, s[22:23] nt
	s_add_u32 s22, s22, 0x5800
	s_addc_u32 s23, s23, 0
	global_load_dwordx4 v[208:211], v190, s[22:23] nt
	s_add_u32 s22, s22, 0x5800
	s_addc_u32 s23, s23, 0
	global_load_dwordx4 v[212:215], v190, s[22:23] nt
	v_lshrrev_b32_e32 v8, 4, v2
	v_and_b32_e32 v3, 15, v2
	v_lshlrev_b32_e32 v3, 2, v3
	v_mul_u32_u24_e32 v8, 0x6000, v8
	v_add_u32_e32 v191, v8, v3
	s_lshl_b32 s19, s17, 6
	s_addk_i32 s19, 0x3000
	v_add_u32_e32 v191, s19, v191
	global_load_dword v189, v191, s[12:13]

.Lp1_nob1:
	s_waitcnt vmcnt(12)
	v_pk_add_f32 v[52:53], v[52:53], v[18:19]
	v_pk_add_f32 v[54:55], v[54:55], v[18:19]
	v_pk_add_f32 v[56:57], v[56:57], v[18:19]
	v_pk_add_f32 v[58:59], v[58:59], v[18:19]
	v_pk_add_f32 v[60:61], v[60:61], v[18:19]
	v_pk_add_f32 v[62:63], v[62:63], v[18:19]
	v_pk_add_f32 v[64:65], v[64:65], v[18:19]
	v_pk_add_f32 v[66:67], v[66:67], v[18:19]
	s_add_u32 s14, s12, 0x6000
	s_addc_u32 s15, s13, 0
	s_add_u32 s16, s14, 0x1000
	s_addc_u32 s17, s15, 0
	global_load_dwordx4 v[148:151], v0, s[14:15] nt
	global_load_dwordx4 v[152:155], v0, s[14:15] offset:1024
	global_load_dwordx4 v[156:159], v0, s[14:15] offset:2048
	global_load_dwordx4 v[160:163], v0, s[14:15] offset:3072
	global_load_dwordx4 v[164:167], v0, s[16:17]
	global_load_dwordx4 v[168:171], v0, s[16:17] offset:1024
	global_load_dwordx4 v[172:175], v0, s[16:17] offset:2048
	global_load_dwordx4 v[176:179], v0, s[16:17] offset:3072
	v_pk_mul_f32 v[4:5], v[68:69], v[68:69]
	v_pk_fma_f32 v[4:5], v[70:71], v[70:71], v[4:5]
	v_pk_fma_f32 v[4:5], v[72:73], v[72:73], v[4:5]
	v_pk_fma_f32 v[4:5], v[74:75], v[74:75], v[4:5]
	v_pk_fma_f32 v[4:5], v[76:77], v[76:77], v[4:5]
	v_pk_fma_f32 v[4:5], v[78:79], v[78:79], v[4:5]
	v_pk_fma_f32 v[4:5], v[80:81], v[80:81], v[4:5]
	v_pk_fma_f32 v[4:5], v[82:83], v[82:83], v[4:5]
	v_add_f32_e32 v4, v4, v5
	s_nop 1
	v_add_f32_dpp v4, v4, v4 quad_perm:[1,0,3,2] row_mask:0xf bank_mask:0xf
	s_nop 1
	v_add_f32_dpp v4, v4, v4 quad_perm:[2,3,0,1] row_mask:0xf bank_mask:0xf
	s_nop 1
	v_add_f32_dpp v4, v4, v4 row_half_mirror row_mask:0xf bank_mask:0xf
	s_nop 1
	v_add_f32_dpp v4, v4, v4 row_mirror row_mask:0xf bank_mask:0xf
	s_nop 1
	v_add_f32_dpp v4, v4, v4 row_bcast:15 row_mask:0xa bank_mask:0xf
	s_nop 1
	v_add_f32_dpp v4, v4, v4 row_bcast:31 row_mask:0xc bank_mask:0xf
	s_nop 1
	v_readlane_b32 s20, v4, 63
	s_nop 1
	v_fma_f32 v6, s20, v16, v17
	v_rsq_f32_e32 v6, v6
	s_nop 0
	v_pk_mul_f32 v[68:69], v[68:69], v[6:7] op_sel_hi:[1,0]
	v_pk_mul_f32 v[70:71], v[70:71], v[6:7] op_sel_hi:[1,0]
	v_pk_mul_f32 v[72:73], v[72:73], v[6:7] op_sel_hi:[1,0]
	v_pk_mul_f32 v[74:75], v[74:75], v[6:7] op_sel_hi:[1,0]
	v_pk_mul_f32 v[76:77], v[76:77], v[6:7] op_sel_hi:[1,0]
	v_pk_mul_f32 v[78:79], v[78:79], v[6:7] op_sel_hi:[1,0]
	v_pk_mul_f32 v[80:81], v[80:81], v[6:7] op_sel_hi:[1,0]
	v_pk_mul_f32 v[82:83], v[82:83], v[6:7] op_sel_hi:[1,0]
	v_pk_mul_f32 v[68:69], v[68:69], v[20:21]
	v_pk_mul_f32 v[70:71], v[70:71], v[22:23]
	v_pk_mul_f32 v[72:73], v[72:73], v[24:25]
	v_pk_mul_f32 v[74:75], v[74:75], v[26:27]
	v_pk_mul_f32 v[76:77], v[76:77], v[28:29]
	v_pk_mul_f32 v[78:79], v[78:79], v[30:31]
	v_pk_mul_f32 v[80:81], v[80:81], v[32:33]
	v_pk_mul_f32 v[82:83], v[82:83], v[34:35]
	v_pk_fma_f32 v[68:69], v[68:69], v[52:53], v[36:37]
	v_pk_fma_f32 v[70:71], v[70:71], v[54:55], v[38:39]
	v_pk_fma_f32 v[72:73], v[72:73], v[56:57], v[40:41]
	v_pk_fma_f32 v[74:75], v[74:75], v[58:59], v[42:43]
	v_pk_fma_f32 v[76:77], v[76:77], v[60:61], v[44:45]
	v_pk_fma_f32 v[78:79], v[78:79], v[62:63], v[46:47]
	v_pk_fma_f32 v[80:81], v[80:81], v[64:65], v[48:49]
	v_pk_fma_f32 v[82:83], v[82:83], v[66:67], v[50:51]
	v_cvt_pk_bf16_f32 v232, v68, v69
	v_cvt_pk_bf16_f32 v233, v70, v71
	v_cvt_pk_bf16_f32 v234, v72, v73
	v_cvt_pk_bf16_f32 v235, v74, v75
	v_cvt_pk_bf16_f32 v236, v76, v77
	v_cvt_pk_bf16_f32 v237, v78, v79
	v_cvt_pk_bf16_f32 v238, v80, v81
	v_cvt_pk_bf16_f32 v239, v82, v83
	global_store_dwordx2 v1, v[232:233], s[10:11]
	global_store_dwordx2 v1, v[234:235], s[10:11] offset:512
	global_store_dwordx2 v1, v[236:237], s[10:11] offset:1024
	global_store_dwordx2 v1, v[238:239], s[10:11] offset:1536
	s_add_u32 s10, s10, 0x400000
	s_addc_u32 s11, s11, 0
	global_load_dwordx4 v[68:71], v0, s[8:9] nt
	global_load_dwordx4 v[72:75], v0, s[8:9] offset:1024 nt
	global_load_dwordx4 v[76:79], v0, s[8:9] offset:2048 nt
	global_load_dwordx4 v[80:83], v0, s[8:9] offset:3072 nt
	s_add_u32 s8, s8, 0x800000
	s_addc_u32 s9, s9, 0
	s_waitcnt vmcnt(24)
	v_pk_mul_f32 v[4:5], v[84:85], v[84:85]
	v_pk_fma_f32 v[4:5], v[86:87], v[86:87], v[4:5]
	v_pk_fma_f32 v[4:5], v[88:89], v[88:89], v[4:5]
	v_pk_fma_f32 v[4:5], v[90:91], v[90:91], v[4:5]
	v_pk_fma_f32 v[4:5], v[92:93], v[92:93], v[4:5]
	v_pk_fma_f32 v[4:5], v[94:95], v[94:95], v[4:5]
	v_pk_fma_f32 v[4:5], v[96:97], v[96:97], v[4:5]
	v_pk_fma_f32 v[4:5], v[98:99], v[98:99], v[4:5]
	v_add_f32_e32 v4, v4, v5
	s_nop 1
	v_add_f32_dpp v4, v4, v4 quad_perm:[1,0,3,2] row_mask:0xf bank_mask:0xf
	s_nop 1
	v_add_f32_dpp v4, v4, v4 quad_perm:[2,3,0,1] row_mask:0xf bank_mask:0xf
	s_nop 1
	v_add_f32_dpp v4, v4, v4 row_half_mirror row_mask:0xf bank_mask:0xf
	s_nop 1
	v_add_f32_dpp v4, v4, v4 row_mirror row_mask:0xf bank_mask:0xf
	s_nop 1
	v_add_f32_dpp v4, v4, v4 row_bcast:15 row_mask:0xa bank_mask:0xf
	s_nop 1
	v_add_f32_dpp v4, v4, v4 row_bcast:31 row_mask:0xc bank_mask:0xf
	s_nop 1
	v_readlane_b32 s20, v4, 63
	s_nop 1
	v_fma_f32 v6, s20, v16, v17
	v_rsq_f32_e32 v6, v6
	s_nop 0
	v_pk_mul_f32 v[84:85], v[84:85], v[6:7] op_sel_hi:[1,0]
	v_pk_mul_f32 v[86:87], v[86:87], v[6:7] op_sel_hi:[1,0]
	v_pk_mul_f32 v[88:89], v[88:89], v[6:7] op_sel_hi:[1,0]
	v_pk_mul_f32 v[90:91], v[90:91], v[6:7] op_sel_hi:[1,0]
	v_pk_mul_f32 v[92:93], v[92:93], v[6:7] op_sel_hi:[1,0]
	v_pk_mul_f32 v[94:95], v[94:95], v[6:7] op_sel_hi:[1,0]
	v_pk_mul_f32 v[96:97], v[96:97], v[6:7] op_sel_hi:[1,0]
	v_pk_mul_f32 v[98:99], v[98:99], v[6:7] op_sel_hi:[1,0]
	v_pk_mul_f32 v[84:85], v[84:85], v[20:21]
	v_pk_mul_f32 v[86:87], v[86:87], v[22:23]
	v_pk_mul_f32 v[88:89], v[88:89], v[24:25]
	v_pk_mul_f32 v[90:91], v[90:91], v[26:27]
	v_pk_mul_f32 v[92:93], v[92:93], v[28:29]
	v_pk_mul_f32 v[94:95], v[94:95], v[30:31]
	v_pk_mul_f32 v[96:97], v[96:97], v[32:33]
	v_pk_mul_f32 v[98:99], v[98:99], v[34:35]
	v_pk_fma_f32 v[84:85], v[84:85], v[52:53], v[36:37]
	v_pk_fma_f32 v[86:87], v[86:87], v[54:55], v[38:39]
	v_pk_fma_f32 v[88:89], v[88:89], v[56:57], v[40:41]
	v_pk_fma_f32 v[90:91], v[90:91], v[58:59], v[42:43]
	v_pk_fma_f32 v[92:93], v[92:93], v[60:61], v[44:45]
	v_pk_fma_f32 v[94:95], v[94:95], v[62:63], v[46:47]
	v_pk_fma_f32 v[96:97], v[96:97], v[64:65], v[48:49]
	v_pk_fma_f32 v[98:99], v[98:99], v[66:67], v[50:51]
	v_cvt_pk_bf16_f32 v240, v84, v85
	v_cvt_pk_bf16_f32 v241, v86, v87
	v_cvt_pk_bf16_f32 v242, v88, v89
	v_cvt_pk_bf16_f32 v243, v90, v91
	v_cvt_pk_bf16_f32 v244, v92, v93
	v_cvt_pk_bf16_f32 v245, v94, v95
	v_cvt_pk_bf16_f32 v246, v96, v97
	v_cvt_pk_bf16_f32 v247, v98, v99
	global_store_dwordx2 v1, v[240:241], s[10:11]
	global_store_dwordx2 v1, v[242:243], s[10:11] offset:512
	global_store_dwordx2 v1, v[244:245], s[10:11] offset:1024
	global_store_dwordx2 v1, v[246:247], s[10:11] offset:1536
	s_add_u32 s10, s10, 0x400000
	s_addc_u32 s11, s11, 0
	global_load_dwordx4 v[84:87], v0, s[8:9] nt
	global_load_dwordx4 v[88:91], v0, s[8:9] offset:1024 nt
	global_load_dwordx4 v[92:95], v0, s[8:9] offset:2048 nt
	global_load_dwordx4 v[96:99], v0, s[8:9] offset:3072 nt
	s_add_u32 s8, s8, 0x800000
	s_addc_u32 s9, s9, 0
	s_waitcnt vmcnt(28)
	v_pk_mul_f32 v[4:5], v[100:101], v[100:101]
	v_pk_fma_f32 v[4:5], v[102:103], v[102:103], v[4:5]
	v_pk_fma_f32 v[4:5], v[104:105], v[104:105], v[4:5]
	v_pk_fma_f32 v[4:5], v[106:107], v[106:107], v[4:5]
	v_pk_fma_f32 v[4:5], v[108:109], v[108:109], v[4:5]
	v_pk_fma_f32 v[4:5], v[110:111], v[110:111], v[4:5]
	v_pk_fma_f32 v[4:5], v[112:113], v[112:113], v[4:5]
	v_pk_fma_f32 v[4:5], v[114:115], v[114:115], v[4:5]
	v_add_f32_e32 v4, v4, v5
	s_nop 1
	v_add_f32_dpp v4, v4, v4 quad_perm:[1,0,3,2] row_mask:0xf bank_mask:0xf
	s_nop 1
	v_add_f32_dpp v4, v4, v4 quad_perm:[2,3,0,1] row_mask:0xf bank_mask:0xf
	s_nop 1
	v_add_f32_dpp v4, v4, v4 row_half_mirror row_mask:0xf bank_mask:0xf
	s_nop 1
	v_add_f32_dpp v4, v4, v4 row_mirror row_mask:0xf bank_mask:0xf
	s_nop 1
	v_add_f32_dpp v4, v4, v4 row_bcast:15 row_mask:0xa bank_mask:0xf
	s_nop 1
	v_add_f32_dpp v4, v4, v4 row_bcast:31 row_mask:0xc bank_mask:0xf
	s_nop 1
	v_readlane_b32 s20, v4, 63
	s_nop 1
	v_fma_f32 v6, s20, v16, v17
	v_rsq_f32_e32 v6, v6
	s_nop 0
	v_pk_mul_f32 v[100:101], v[100:101], v[6:7] op_sel_hi:[1,0]
	v_pk_mul_f32 v[102:103], v[102:103], v[6:7] op_sel_hi:[1,0]
	v_pk_mul_f32 v[104:105], v[104:105], v[6:7] op_sel_hi:[1,0]
	v_pk_mul_f32 v[106:107], v[106:107], v[6:7] op_sel_hi:[1,0]
	v_pk_mul_f32 v[108:109], v[108:109], v[6:7] op_sel_hi:[1,0]
	v_pk_mul_f32 v[110:111], v[110:111], v[6:7] op_sel_hi:[1,0]
	v_pk_mul_f32 v[112:113], v[112:113], v[6:7] op_sel_hi:[1,0]
	v_pk_mul_f32 v[114:115], v[114:115], v[6:7] op_sel_hi:[1,0]
	v_pk_mul_f32 v[100:101], v[100:101], v[20:21]
	v_pk_mul_f32 v[102:103], v[102:103], v[22:23]
	v_pk_mul_f32 v[104:105], v[104:105], v[24:25]
	v_pk_mul_f32 v[106:107], v[106:107], v[26:27]
	v_pk_mul_f32 v[108:109], v[108:109], v[28:29]
	v_pk_mul_f32 v[110:111], v[110:111], v[30:31]
	v_pk_mul_f32 v[112:113], v[112:113], v[32:33]
	v_pk_mul_f32 v[114:115], v[114:115], v[34:35]
	v_pk_fma_f32 v[100:101], v[100:101], v[52:53], v[36:37]
	v_pk_fma_f32 v[102:103], v[102:103], v[54:55], v[38:39]
	v_pk_fma_f32 v[104:105], v[104:105], v[56:57], v[40:41]
	v_pk_fma_f32 v[106:107], v[106:107], v[58:59], v[42:43]
	v_pk_fma_f32 v[108:109], v[108:109], v[60:61], v[44:45]
	v_pk_fma_f32 v[110:111], v[110:111], v[62:63], v[46:47]
	v_pk_fma_f32 v[112:113], v[112:113], v[64:65], v[48:49]
	v_pk_fma_f32 v[114:115], v[114:115], v[66:67], v[50:51]
	v_cvt_pk_bf16_f32 v232, v100, v101
	v_cvt_pk_bf16_f32 v233, v102, v103
	v_cvt_pk_bf16_f32 v234, v104, v105
	v_cvt_pk_bf16_f32 v235, v106, v107
	v_cvt_pk_bf16_f32 v236, v108, v109
	v_cvt_pk_bf16_f32 v237, v110, v111
	v_cvt_pk_bf16_f32 v238, v112, v113
	v_cvt_pk_bf16_f32 v239, v114, v115
	global_store_dwordx2 v1, v[232:233], s[10:11]
	global_store_dwordx2 v1, v[234:235], s[10:11] offset:512
	global_store_dwordx2 v1, v[236:237], s[10:11] offset:1024
	global_store_dwordx2 v1, v[238:239], s[10:11] offset:1536
	s_add_u32 s10, s10, 0x400000
	s_addc_u32 s11, s11, 0
	global_load_dwordx4 v[100:103], v0, s[8:9] nt
	global_load_dwordx4 v[104:107], v0, s[8:9] offset:1024 nt
	global_load_dwordx4 v[108:111], v0, s[8:9] offset:2048 nt
	global_load_dwordx4 v[112:115], v0, s[8:9] offset:3072 nt
	s_add_u32 s8, s8, 0x800000
	s_addc_u32 s9, s9, 0
	s_waitcnt vmcnt(32)
	v_pk_mul_f32 v[4:5], v[116:117], v[116:117]
	v_pk_fma_f32 v[4:5], v[118:119], v[118:119], v[4:5]
	v_pk_fma_f32 v[4:5], v[120:121], v[120:121], v[4:5]
	v_pk_fma_f32 v[4:5], v[122:123], v[122:123], v[4:5]
	v_pk_fma_f32 v[4:5], v[124:125], v[124:125], v[4:5]
	v_pk_fma_f32 v[4:5], v[126:127], v[126:127], v[4:5]
	v_pk_fma_f32 v[4:5], v[128:129], v[128:129], v[4:5]
	v_pk_fma_f32 v[4:5], v[130:131], v[130:131], v[4:5]
	v_add_f32_e32 v4, v4, v5
	s_nop 1
	v_add_f32_dpp v4, v4, v4 quad_perm:[1,0,3,2] row_mask:0xf bank_mask:0xf
	s_nop 1
	v_add_f32_dpp v4, v4, v4 quad_perm:[2,3,0,1] row_mask:0xf bank_mask:0xf
	s_nop 1
	v_add_f32_dpp v4, v4, v4 row_half_mirror row_mask:0xf bank_mask:0xf
	s_nop 1
	v_add_f32_dpp v4, v4, v4 row_mirror row_mask:0xf bank_mask:0xf
	s_nop 1
	v_add_f32_dpp v4, v4, v4 row_bcast:15 row_mask:0xa bank_mask:0xf
	s_nop 1
	v_add_f32_dpp v4, v4, v4 row_bcast:31 row_mask:0xc bank_mask:0xf
	s_nop 1
	v_readlane_b32 s20, v4, 63
	s_nop 1
	v_fma_f32 v6, s20, v16, v17
	v_rsq_f32_e32 v6, v6
	s_nop 0
	v_pk_mul_f32 v[116:117], v[116:117], v[6:7] op_sel_hi:[1,0]
	v_pk_mul_f32 v[118:119], v[118:119], v[6:7] op_sel_hi:[1,0]
	v_pk_mul_f32 v[120:121], v[120:121], v[6:7] op_sel_hi:[1,0]
	v_pk_mul_f32 v[122:123], v[122:123], v[6:7] op_sel_hi:[1,0]
	v_pk_mul_f32 v[124:125], v[124:125], v[6:7] op_sel_hi:[1,0]
	v_pk_mul_f32 v[126:127], v[126:127], v[6:7] op_sel_hi:[1,0]
	v_pk_mul_f32 v[128:129], v[128:129], v[6:7] op_sel_hi:[1,0]
	v_pk_mul_f32 v[130:131], v[130:131], v[6:7] op_sel_hi:[1,0]
	v_pk_mul_f32 v[116:117], v[116:117], v[20:21]
	v_pk_mul_f32 v[118:119], v[118:119], v[22:23]
	v_pk_mul_f32 v[120:121], v[120:121], v[24:25]
	v_pk_mul_f32 v[122:123], v[122:123], v[26:27]
	v_pk_mul_f32 v[124:125], v[124:125], v[28:29]
	v_pk_mul_f32 v[126:127], v[126:127], v[30:31]
	v_pk_mul_f32 v[128:129], v[128:129], v[32:33]
	v_pk_mul_f32 v[130:131], v[130:131], v[34:35]
	v_pk_fma_f32 v[116:117], v[116:117], v[52:53], v[36:37]
	v_pk_fma_f32 v[118:119], v[118:119], v[54:55], v[38:39]
	v_pk_fma_f32 v[120:121], v[120:121], v[56:57], v[40:41]
	v_pk_fma_f32 v[122:123], v[122:123], v[58:59], v[42:43]
	v_pk_fma_f32 v[124:125], v[124:125], v[60:61], v[44:45]
	v_pk_fma_f32 v[126:127], v[126:127], v[62:63], v[46:47]
	v_pk_fma_f32 v[128:129], v[128:129], v[64:65], v[48:49]
	v_pk_fma_f32 v[130:131], v[130:131], v[66:67], v[50:51]
	v_cvt_pk_bf16_f32 v240, v116, v117
	v_cvt_pk_bf16_f32 v241, v118, v119
	v_cvt_pk_bf16_f32 v242, v120, v121
	v_cvt_pk_bf16_f32 v243, v122, v123
	v_cvt_pk_bf16_f32 v244, v124, v125
	v_cvt_pk_bf16_f32 v245, v126, v127
	v_cvt_pk_bf16_f32 v246, v128, v129
	v_cvt_pk_bf16_f32 v247, v130, v131
	global_store_dwordx2 v1, v[240:241], s[10:11]
	global_store_dwordx2 v1, v[242:243], s[10:11] offset:512
	global_store_dwordx2 v1, v[244:245], s[10:11] offset:1024
	global_store_dwordx2 v1, v[246:247], s[10:11] offset:1536
	s_add_u32 s10, s10, 0x400000
	s_addc_u32 s11, s11, 0
	global_load_dwordx4 v[116:119], v0, s[8:9] nt
	global_load_dwordx4 v[120:123], v0, s[8:9] offset:1024 nt
	global_load_dwordx4 v[124:127], v0, s[8:9] offset:2048 nt
	global_load_dwordx4 v[128:131], v0, s[8:9] offset:3072 nt
	s_add_u32 s8, s8, 0x800000
	s_addc_u32 s9, s9, 0
	s_waitcnt vmcnt(24)
	v_pk_add_f32 v[164:165], v[164:165], v[18:19]
	v_pk_add_f32 v[166:167], v[166:167], v[18:19]
	v_pk_add_f32 v[168:169], v[168:169], v[18:19]
	v_pk_add_f32 v[170:171], v[170:171], v[18:19]
	v_pk_add_f32 v[172:173], v[172:173], v[18:19]
	v_pk_add_f32 v[174:175], v[174:175], v[18:19]
	v_pk_add_f32 v[176:177], v[176:177], v[18:19]
	v_pk_add_f32 v[178:179], v[178:179], v[18:19]
	s_add_u32 s14, s12, 0xc000
	s_addc_u32 s15, s13, 0
	s_add_u32 s16, s14, 0x1000
	s_addc_u32 s17, s15, 0
	global_load_dwordx4 v[36:39], v0, s[14:15]
	global_load_dwordx4 v[40:43], v0, s[14:15] offset:1024
	global_load_dwordx4 v[44:47], v0, s[14:15] offset:2048
	global_load_dwordx4 v[48:51], v0, s[14:15] offset:3072
	global_load_dwordx4 v[52:55], v0, s[16:17]
	global_load_dwordx4 v[56:59], v0, s[16:17] offset:1024
	global_load_dwordx4 v[60:63], v0, s[16:17] offset:2048
	global_load_dwordx4 v[64:67], v0, s[16:17] offset:3072
	v_pk_mul_f32 v[4:5], v[68:69], v[68:69]
	v_pk_fma_f32 v[4:5], v[70:71], v[70:71], v[4:5]
	v_pk_fma_f32 v[4:5], v[72:73], v[72:73], v[4:5]
	v_pk_fma_f32 v[4:5], v[74:75], v[74:75], v[4:5]
	v_pk_fma_f32 v[4:5], v[76:77], v[76:77], v[4:5]
	v_pk_fma_f32 v[4:5], v[78:79], v[78:79], v[4:5]
	v_pk_fma_f32 v[4:5], v[80:81], v[80:81], v[4:5]
	v_pk_fma_f32 v[4:5], v[82:83], v[82:83], v[4:5]
	v_add_f32_e32 v4, v4, v5
	s_nop 1
	v_add_f32_dpp v4, v4, v4 quad_perm:[1,0,3,2] row_mask:0xf bank_mask:0xf
	s_nop 1
	v_add_f32_dpp v4, v4, v4 quad_perm:[2,3,0,1] row_mask:0xf bank_mask:0xf
	s_nop 1
	v_add_f32_dpp v4, v4, v4 row_half_mirror row_mask:0xf bank_mask:0xf
	s_nop 1
	v_add_f32_dpp v4, v4, v4 row_mirror row_mask:0xf bank_mask:0xf
	s_nop 1
	v_add_f32_dpp v4, v4, v4 row_bcast:15 row_mask:0xa bank_mask:0xf
	s_nop 1
	v_add_f32_dpp v4, v4, v4 row_bcast:31 row_mask:0xc bank_mask:0xf
	s_nop 1
	v_readlane_b32 s20, v4, 63
	s_nop 1
	v_fma_f32 v6, s20, v16, v17
	v_rsq_f32_e32 v6, v6
	s_nop 0
	v_pk_mul_f32 v[68:69], v[68:69], v[6:7] op_sel_hi:[1,0]
	v_pk_mul_f32 v[70:71], v[70:71], v[6:7] op_sel_hi:[1,0]
	v_pk_mul_f32 v[72:73], v[72:73], v[6:7] op_sel_hi:[1,0]
	v_pk_mul_f32 v[74:75], v[74:75], v[6:7] op_sel_hi:[1,0]
	v_pk_mul_f32 v[76:77], v[76:77], v[6:7] op_sel_hi:[1,0]
	v_pk_mul_f32 v[78:79], v[78:79], v[6:7] op_sel_hi:[1,0]
	v_pk_mul_f32 v[80:81], v[80:81], v[6:7] op_sel_hi:[1,0]
	v_pk_mul_f32 v[82:83], v[82:83], v[6:7] op_sel_hi:[1,0]
	v_pk_mul_f32 v[68:69], v[68:69], v[20:21]
	v_pk_mul_f32 v[70:71], v[70:71], v[22:23]
	v_pk_mul_f32 v[72:73], v[72:73], v[24:25]
	v_pk_mul_f32 v[74:75], v[74:75], v[26:27]
	v_pk_mul_f32 v[76:77], v[76:77], v[28:29]
	v_pk_mul_f32 v[78:79], v[78:79], v[30:31]
	v_pk_mul_f32 v[80:81], v[80:81], v[32:33]
	v_pk_mul_f32 v[82:83], v[82:83], v[34:35]
	v_pk_fma_f32 v[68:69], v[68:69], v[164:165], v[148:149]
	v_pk_fma_f32 v[70:71], v[70:71], v[166:167], v[150:151]
	v_pk_fma_f32 v[72:73], v[72:73], v[168:169], v[152:153]
	v_pk_fma_f32 v[74:75], v[74:75], v[170:171], v[154:155]
	v_pk_fma_f32 v[76:77], v[76:77], v[172:173], v[156:157]
	v_pk_fma_f32 v[78:79], v[78:79], v[174:175], v[158:159]
	v_pk_fma_f32 v[80:81], v[80:81], v[176:177], v[160:161]
	v_pk_fma_f32 v[82:83], v[82:83], v[178:179], v[162:163]
	v_cvt_pk_bf16_f32 v232, v68, v69
	v_cvt_pk_bf16_f32 v233, v70, v71
	v_cvt_pk_bf16_f32 v234, v72, v73
	v_cvt_pk_bf16_f32 v235, v74, v75
	v_cvt_pk_bf16_f32 v236, v76, v77
	v_cvt_pk_bf16_f32 v237, v78, v79
	v_cvt_pk_bf16_f32 v238, v80, v81
	v_cvt_pk_bf16_f32 v239, v82, v83
	global_store_dwordx2 v1, v[232:233], s[10:11]
	global_store_dwordx2 v1, v[234:235], s[10:11] offset:512
	global_store_dwordx2 v1, v[236:237], s[10:11] offset:1024
	global_store_dwordx2 v1, v[238:239], s[10:11] offset:1536
	s_add_u32 s10, s10, 0x400000
	s_addc_u32 s11, s11, 0
	global_load_dwordx4 v[68:71], v0, s[8:9] nt
	global_load_dwordx4 v[72:75], v0, s[8:9] offset:1024 nt
	global_load_dwordx4 v[76:79], v0, s[8:9] offset:2048 nt
	global_load_dwordx4 v[80:83], v0, s[8:9] offset:3072 nt
	s_add_u32 s8, s8, 0x800000
	s_addc_u32 s9, s9, 0
	s_waitcnt vmcnt(32)
	v_pk_mul_f32 v[4:5], v[84:85], v[84:85]
	v_pk_fma_f32 v[4:5], v[86:87], v[86:87], v[4:5]
	v_pk_fma_f32 v[4:5], v[88:89], v[88:89], v[4:5]
	v_pk_fma_f32 v[4:5], v[90:91], v[90:91], v[4:5]
	v_pk_fma_f32 v[4:5], v[92:93], v[92:93], v[4:5]
	v_pk_fma_f32 v[4:5], v[94:95], v[94:95], v[4:5]
	v_pk_fma_f32 v[4:5], v[96:97], v[96:97], v[4:5]
	v_pk_fma_f32 v[4:5], v[98:99], v[98:99], v[4:5]
	v_add_f32_e32 v4, v4, v5
	s_nop 1
	v_add_f32_dpp v4, v4, v4 quad_perm:[1,0,3,2] row_mask:0xf bank_mask:0xf
	s_nop 1
	v_add_f32_dpp v4, v4, v4 quad_perm:[2,3,0,1] row_mask:0xf bank_mask:0xf
	s_nop 1
	v_add_f32_dpp v4, v4, v4 row_half_mirror row_mask:0xf bank_mask:0xf
	s_nop 1
	v_add_f32_dpp v4, v4, v4 row_mirror row_mask:0xf bank_mask:0xf
	s_nop 1
	v_add_f32_dpp v4, v4, v4 row_bcast:15 row_mask:0xa bank_mask:0xf
	s_nop 1
	v_add_f32_dpp v4, v4, v4 row_bcast:31 row_mask:0xc bank_mask:0xf
	s_nop 1
	v_readlane_b32 s20, v4, 63
	s_nop 1
	v_fma_f32 v6, s20, v16, v17
	v_rsq_f32_e32 v6, v6
	s_nop 0
	v_pk_mul_f32 v[84:85], v[84:85], v[6:7] op_sel_hi:[1,0]
	v_pk_mul_f32 v[86:87], v[86:87], v[6:7] op_sel_hi:[1,0]
	v_pk_mul_f32 v[88:89], v[88:89], v[6:7] op_sel_hi:[1,0]
	v_pk_mul_f32 v[90:91], v[90:91], v[6:7] op_sel_hi:[1,0]
	v_pk_mul_f32 v[92:93], v[92:93], v[6:7] op_sel_hi:[1,0]
	v_pk_mul_f32 v[94:95], v[94:95], v[6:7] op_sel_hi:[1,0]
	v_pk_mul_f32 v[96:97], v[96:97], v[6:7] op_sel_hi:[1,0]
	v_pk_mul_f32 v[98:99], v[98:99], v[6:7] op_sel_hi:[1,0]
	v_pk_mul_f32 v[84:85], v[84:85], v[20:21]
	v_pk_mul_f32 v[86:87], v[86:87], v[22:23]
	v_pk_mul_f32 v[88:89], v[88:89], v[24:25]
	v_pk_mul_f32 v[90:91], v[90:91], v[26:27]
	v_pk_mul_f32 v[92:93], v[92:93], v[28:29]
	v_pk_mul_f32 v[94:95], v[94:95], v[30:31]
	v_pk_mul_f32 v[96:97], v[96:97], v[32:33]
	v_pk_mul_f32 v[98:99], v[98:99], v[34:35]
	v_pk_fma_f32 v[84:85], v[84:85], v[164:165], v[148:149]
	v_pk_fma_f32 v[86:87], v[86:87], v[166:167], v[150:151]
	v_pk_fma_f32 v[88:89], v[88:89], v[168:169], v[152:153]
	v_pk_fma_f32 v[90:91], v[90:91], v[170:171], v[154:155]
	v_pk_fma_f32 v[92:93], v[92:93], v[172:173], v[156:157]
	v_pk_fma_f32 v[94:95], v[94:95], v[174:175], v[158:159]
	v_pk_fma_f32 v[96:97], v[96:97], v[176:177], v[160:161]
	v_pk_fma_f32 v[98:99], v[98:99], v[178:179], v[162:163]
	v_cvt_pk_bf16_f32 v240, v84, v85
	v_cvt_pk_bf16_f32 v241, v86, v87
	v_cvt_pk_bf16_f32 v242, v88, v89
	v_cvt_pk_bf16_f32 v243, v90, v91
	v_cvt_pk_bf16_f32 v244, v92, v93
	v_cvt_pk_bf16_f32 v245, v94, v95
	v_cvt_pk_bf16_f32 v246, v96, v97
	v_cvt_pk_bf16_f32 v247, v98, v99
	global_store_dwordx2 v1, v[240:241], s[10:11]
	global_store_dwordx2 v1, v[242:243], s[10:11] offset:512
	global_store_dwordx2 v1, v[244:245], s[10:11] offset:1024
	global_store_dwordx2 v1, v[246:247], s[10:11] offset:1536
	s_add_u32 s10, s10, 0x400000
	s_addc_u32 s11, s11, 0
	global_load_dwordx4 v[84:87], v0, s[8:9] nt
	global_load_dwordx4 v[88:91], v0, s[8:9] offset:1024 nt
	global_load_dwordx4 v[92:95], v0, s[8:9] offset:2048 nt
	global_load_dwordx4 v[96:99], v0, s[8:9] offset:3072 nt
	s_add_u32 s8, s8, 0x800000
	s_addc_u32 s9, s9, 0
	s_waitcnt vmcnt(32)
	v_pk_mul_f32 v[4:5], v[100:101], v[100:101]
	v_pk_fma_f32 v[4:5], v[102:103], v[102:103], v[4:5]
	v_pk_fma_f32 v[4:5], v[104:105], v[104:105], v[4:5]
	v_pk_fma_f32 v[4:5], v[106:107], v[106:107], v[4:5]
	v_pk_fma_f32 v[4:5], v[108:109], v[108:109], v[4:5]
	v_pk_fma_f32 v[4:5], v[110:111], v[110:111], v[4:5]
	v_pk_fma_f32 v[4:5], v[112:113], v[112:113], v[4:5]
	v_pk_fma_f32 v[4:5], v[114:115], v[114:115], v[4:5]
	v_add_f32_e32 v4, v4, v5
	s_nop 1
	v_add_f32_dpp v4, v4, v4 quad_perm:[1,0,3,2] row_mask:0xf bank_mask:0xf
	s_nop 1
	v_add_f32_dpp v4, v4, v4 quad_perm:[2,3,0,1] row_mask:0xf bank_mask:0xf
	s_nop 1
	v_add_f32_dpp v4, v4, v4 row_half_mirror row_mask:0xf bank_mask:0xf
	s_nop 1
	v_add_f32_dpp v4, v4, v4 row_mirror row_mask:0xf bank_mask:0xf
	s_nop 1
	v_add_f32_dpp v4, v4, v4 row_bcast:15 row_mask:0xa bank_mask:0xf
	s_nop 1
	v_add_f32_dpp v4, v4, v4 row_bcast:31 row_mask:0xc bank_mask:0xf
	s_nop 1
	v_readlane_b32 s20, v4, 63
	s_nop 1
	v_fma_f32 v6, s20, v16, v17
	v_rsq_f32_e32 v6, v6
	s_nop 0
	v_pk_mul_f32 v[100:101], v[100:101], v[6:7] op_sel_hi:[1,0]
	v_pk_mul_f32 v[102:103], v[102:103], v[6:7] op_sel_hi:[1,0]
	v_pk_mul_f32 v[104:105], v[104:105], v[6:7] op_sel_hi:[1,0]
	v_pk_mul_f32 v[106:107], v[106:107], v[6:7] op_sel_hi:[1,0]
	v_pk_mul_f32 v[108:109], v[108:109], v[6:7] op_sel_hi:[1,0]
	v_pk_mul_f32 v[110:111], v[110:111], v[6:7] op_sel_hi:[1,0]
	v_pk_mul_f32 v[112:113], v[112:113], v[6:7] op_sel_hi:[1,0]
	v_pk_mul_f32 v[114:115], v[114:115], v[6:7] op_sel_hi:[1,0]
	v_pk_mul_f32 v[100:101], v[100:101], v[20:21]
	v_pk_mul_f32 v[102:103], v[102:103], v[22:23]
	v_pk_mul_f32 v[104:105], v[104:105], v[24:25]
	v_pk_mul_f32 v[106:107], v[106:107], v[26:27]
	v_pk_mul_f32 v[108:109], v[108:109], v[28:29]
	v_pk_mul_f32 v[110:111], v[110:111], v[30:31]
	v_pk_mul_f32 v[112:113], v[112:113], v[32:33]
	v_pk_mul_f32 v[114:115], v[114:115], v[34:35]
	v_pk_fma_f32 v[100:101], v[100:101], v[164:165], v[148:149]
	v_pk_fma_f32 v[102:103], v[102:103], v[166:167], v[150:151]
	v_pk_fma_f32 v[104:105], v[104:105], v[168:169], v[152:153]
	v_pk_fma_f32 v[106:107], v[106:107], v[170:171], v[154:155]
	v_pk_fma_f32 v[108:109], v[108:109], v[172:173], v[156:157]
	v_pk_fma_f32 v[110:111], v[110:111], v[174:175], v[158:159]
	v_pk_fma_f32 v[112:113], v[112:113], v[176:177], v[160:161]
	v_pk_fma_f32 v[114:115], v[114:115], v[178:179], v[162:163]
	v_cvt_pk_bf16_f32 v232, v100, v101
	v_cvt_pk_bf16_f32 v233, v102, v103
	v_cvt_pk_bf16_f32 v234, v104, v105
	v_cvt_pk_bf16_f32 v235, v106, v107
	v_cvt_pk_bf16_f32 v236, v108, v109
	v_cvt_pk_bf16_f32 v237, v110, v111
	v_cvt_pk_bf16_f32 v238, v112, v113
	v_cvt_pk_bf16_f32 v239, v114, v115
	global_store_dwordx2 v1, v[232:233], s[10:11]
	global_store_dwordx2 v1, v[234:235], s[10:11] offset:512
	global_store_dwordx2 v1, v[236:237], s[10:11] offset:1024
	global_store_dwordx2 v1, v[238:239], s[10:11] offset:1536
	s_add_u32 s10, s10, 0x400000
	s_addc_u32 s11, s11, 0
	global_load_dwordx4 v[100:103], v0, s[8:9] nt
	global_load_dwordx4 v[104:107], v0, s[8:9] offset:1024 nt
	global_load_dwordx4 v[108:111], v0, s[8:9] offset:2048 nt
	global_load_dwordx4 v[112:115], v0, s[8:9] offset:3072 nt
	s_add_u32 s8, s8, 0x800000
	s_addc_u32 s9, s9, 0
	s_waitcnt vmcnt(32)
	v_pk_mul_f32 v[4:5], v[116:117], v[116:117]
	v_pk_fma_f32 v[4:5], v[118:119], v[118:119], v[4:5]
	v_pk_fma_f32 v[4:5], v[120:121], v[120:121], v[4:5]
	v_pk_fma_f32 v[4:5], v[122:123], v[122:123], v[4:5]
	v_pk_fma_f32 v[4:5], v[124:125], v[124:125], v[4:5]
	v_pk_fma_f32 v[4:5], v[126:127], v[126:127], v[4:5]
	v_pk_fma_f32 v[4:5], v[128:129], v[128:129], v[4:5]
	v_pk_fma_f32 v[4:5], v[130:131], v[130:131], v[4:5]
	v_add_f32_e32 v4, v4, v5
	s_nop 1
	v_add_f32_dpp v4, v4, v4 quad_perm:[1,0,3,2] row_mask:0xf bank_mask:0xf
	s_nop 1
	v_add_f32_dpp v4, v4, v4 quad_perm:[2,3,0,1] row_mask:0xf bank_mask:0xf
	s_nop 1
	v_add_f32_dpp v4, v4, v4 row_half_mirror row_mask:0xf bank_mask:0xf
	s_nop 1
	v_add_f32_dpp v4, v4, v4 row_mirror row_mask:0xf bank_mask:0xf
	s_nop 1
	v_add_f32_dpp v4, v4, v4 row_bcast:15 row_mask:0xa bank_mask:0xf
	s_nop 1
	v_add_f32_dpp v4, v4, v4 row_bcast:31 row_mask:0xc bank_mask:0xf
	s_nop 1
	v_readlane_b32 s20, v4, 63
	s_nop 1
	v_fma_f32 v6, s20, v16, v17
	v_rsq_f32_e32 v6, v6
	s_nop 0
	v_pk_mul_f32 v[116:117], v[116:117], v[6:7] op_sel_hi:[1,0]
	v_pk_mul_f32 v[118:119], v[118:119], v[6:7] op_sel_hi:[1,0]
	v_pk_mul_f32 v[120:121], v[120:121], v[6:7] op_sel_hi:[1,0]
	v_pk_mul_f32 v[122:123], v[122:123], v[6:7] op_sel_hi:[1,0]
	v_pk_mul_f32 v[124:125], v[124:125], v[6:7] op_sel_hi:[1,0]
	v_pk_mul_f32 v[126:127], v[126:127], v[6:7] op_sel_hi:[1,0]
	v_pk_mul_f32 v[128:129], v[128:129], v[6:7] op_sel_hi:[1,0]
	v_pk_mul_f32 v[130:131], v[130:131], v[6:7] op_sel_hi:[1,0]
	v_pk_mul_f32 v[116:117], v[116:117], v[20:21]
	v_pk_mul_f32 v[118:119], v[118:119], v[22:23]
	v_pk_mul_f32 v[120:121], v[120:121], v[24:25]
	v_pk_mul_f32 v[122:123], v[122:123], v[26:27]
	v_pk_mul_f32 v[124:125], v[124:125], v[28:29]
	v_pk_mul_f32 v[126:127], v[126:127], v[30:31]
	v_pk_mul_f32 v[128:129], v[128:129], v[32:33]
	v_pk_mul_f32 v[130:131], v[130:131], v[34:35]
	v_pk_fma_f32 v[116:117], v[116:117], v[164:165], v[148:149]
	v_pk_fma_f32 v[118:119], v[118:119], v[166:167], v[150:151]
	v_pk_fma_f32 v[120:121], v[120:121], v[168:169], v[152:153]
	v_pk_fma_f32 v[122:123], v[122:123], v[170:171], v[154:155]
	v_pk_fma_f32 v[124:125], v[124:125], v[172:173], v[156:157]
	v_pk_fma_f32 v[126:127], v[126:127], v[174:175], v[158:159]
	v_pk_fma_f32 v[128:129], v[128:129], v[176:177], v[160:161]
	v_pk_fma_f32 v[130:131], v[130:131], v[178:179], v[162:163]
	v_cvt_pk_bf16_f32 v240, v116, v117
	v_cvt_pk_bf16_f32 v241, v118, v119
	v_cvt_pk_bf16_f32 v242, v120, v121
	v_cvt_pk_bf16_f32 v243, v122, v123
	v_cvt_pk_bf16_f32 v244, v124, v125
	v_cvt_pk_bf16_f32 v245, v126, v127
	v_cvt_pk_bf16_f32 v246, v128, v129
	v_cvt_pk_bf16_f32 v247, v130, v131
	global_store_dwordx2 v1, v[240:241], s[10:11]
	global_store_dwordx2 v1, v[242:243], s[10:11] offset:512
	global_store_dwordx2 v1, v[244:245], s[10:11] offset:1024
	global_store_dwordx2 v1, v[246:247], s[10:11] offset:1536
	s_add_u32 s10, s10, 0x400000
	s_addc_u32 s11, s11, 0
	global_load_dwordx4 v[116:119], v0, s[8:9] nt
	global_load_dwordx4 v[120:123], v0, s[8:9] offset:1024 nt
	global_load_dwordx4 v[124:127], v0, s[8:9] offset:2048 nt
	global_load_dwordx4 v[128:131], v0, s[8:9] offset:3072 nt
	s_add_u32 s8, s8, 0x800000
	s_addc_u32 s9, s9, 0
	s_waitcnt vmcnt(24)
	v_pk_add_f32 v[52:53], v[52:53], v[18:19]
	v_pk_add_f32 v[54:55], v[54:55], v[18:19]
	v_pk_add_f32 v[56:57], v[56:57], v[18:19]
	v_pk_add_f32 v[58:59], v[58:59], v[18:19]
	v_pk_add_f32 v[60:61], v[60:61], v[18:19]
	v_pk_add_f32 v[62:63], v[62:63], v[18:19]
	v_pk_add_f32 v[64:65], v[64:65], v[18:19]
	v_pk_add_f32 v[66:67], v[66:67], v[18:19]
	s_add_u32 s14, s12, 0x12000
	s_addc_u32 s15, s13, 0
	s_add_u32 s16, s14, 0x1000
	s_addc_u32 s17, s15, 0
	global_load_dwordx4 v[148:151], v0, s[14:15] nt
	global_load_dwordx4 v[152:155], v0, s[14:15] offset:1024
	global_load_dwordx4 v[156:159], v0, s[14:15] offset:2048
	global_load_dwordx4 v[160:163], v0, s[14:15] offset:3072
	global_load_dwordx4 v[164:167], v0, s[16:17]
	global_load_dwordx4 v[168:171], v0, s[16:17] offset:1024
	global_load_dwordx4 v[172:175], v0, s[16:17] offset:2048
	global_load_dwordx4 v[176:179], v0, s[16:17] offset:3072
	v_pk_mul_f32 v[4:5], v[68:69], v[68:69]
	v_pk_fma_f32 v[4:5], v[70:71], v[70:71], v[4:5]
	v_pk_fma_f32 v[4:5], v[72:73], v[72:73], v[4:5]
	v_pk_fma_f32 v[4:5], v[74:75], v[74:75], v[4:5]
	v_pk_fma_f32 v[4:5], v[76:77], v[76:77], v[4:5]
	v_pk_fma_f32 v[4:5], v[78:79], v[78:79], v[4:5]
	v_pk_fma_f32 v[4:5], v[80:81], v[80:81], v[4:5]
	v_pk_fma_f32 v[4:5], v[82:83], v[82:83], v[4:5]
	v_add_f32_e32 v4, v4, v5
	s_nop 1
	v_add_f32_dpp v4, v4, v4 quad_perm:[1,0,3,2] row_mask:0xf bank_mask:0xf
	s_nop 1
	v_add_f32_dpp v4, v4, v4 quad_perm:[2,3,0,1] row_mask:0xf bank_mask:0xf
	s_nop 1
	v_add_f32_dpp v4, v4, v4 row_half_mirror row_mask:0xf bank_mask:0xf
	s_nop 1
	v_add_f32_dpp v4, v4, v4 row_mirror row_mask:0xf bank_mask:0xf
	s_nop 1
	v_add_f32_dpp v4, v4, v4 row_bcast:15 row_mask:0xa bank_mask:0xf
	s_nop 1
	v_add_f32_dpp v4, v4, v4 row_bcast:31 row_mask:0xc bank_mask:0xf
	s_nop 1
	v_readlane_b32 s20, v4, 63
	s_nop 1
	v_fma_f32 v6, s20, v16, v17
	v_rsq_f32_e32 v6, v6
	s_nop 0
	v_pk_mul_f32 v[68:69], v[68:69], v[6:7] op_sel_hi:[1,0]
	v_pk_mul_f32 v[70:71], v[70:71], v[6:7] op_sel_hi:[1,0]
	v_pk_mul_f32 v[72:73], v[72:73], v[6:7] op_sel_hi:[1,0]
	v_pk_mul_f32 v[74:75], v[74:75], v[6:7] op_sel_hi:[1,0]
	v_pk_mul_f32 v[76:77], v[76:77], v[6:7] op_sel_hi:[1,0]
	v_pk_mul_f32 v[78:79], v[78:79], v[6:7] op_sel_hi:[1,0]
	v_pk_mul_f32 v[80:81], v[80:81], v[6:7] op_sel_hi:[1,0]
	v_pk_mul_f32 v[82:83], v[82:83], v[6:7] op_sel_hi:[1,0]
	v_pk_mul_f32 v[68:69], v[68:69], v[20:21]
	v_pk_mul_f32 v[70:71], v[70:71], v[22:23]
	v_pk_mul_f32 v[72:73], v[72:73], v[24:25]
	v_pk_mul_f32 v[74:75], v[74:75], v[26:27]
	v_pk_mul_f32 v[76:77], v[76:77], v[28:29]
	v_pk_mul_f32 v[78:79], v[78:79], v[30:31]
	v_pk_mul_f32 v[80:81], v[80:81], v[32:33]
	v_pk_mul_f32 v[82:83], v[82:83], v[34:35]
	v_pk_fma_f32 v[68:69], v[68:69], v[52:53], v[36:37]
	v_pk_fma_f32 v[70:71], v[70:71], v[54:55], v[38:39]
	v_pk_fma_f32 v[72:73], v[72:73], v[56:57], v[40:41]
	v_pk_fma_f32 v[74:75], v[74:75], v[58:59], v[42:43]
	v_pk_fma_f32 v[76:77], v[76:77], v[60:61], v[44:45]
	v_pk_fma_f32 v[78:79], v[78:79], v[62:63], v[46:47]
	v_pk_fma_f32 v[80:81], v[80:81], v[64:65], v[48:49]
	v_pk_fma_f32 v[82:83], v[82:83], v[66:67], v[50:51]
	v_cvt_pk_bf16_f32 v232, v68, v69
	v_cvt_pk_bf16_f32 v233, v70, v71
	v_cvt_pk_bf16_f32 v234, v72, v73
	v_cvt_pk_bf16_f32 v235, v74, v75
	v_cvt_pk_bf16_f32 v236, v76, v77
	v_cvt_pk_bf16_f32 v237, v78, v79
	v_cvt_pk_bf16_f32 v238, v80, v81
	v_cvt_pk_bf16_f32 v239, v82, v83
	global_store_dwordx2 v1, v[232:233], s[10:11]
	global_store_dwordx2 v1, v[234:235], s[10:11] offset:512
	global_store_dwordx2 v1, v[236:237], s[10:11] offset:1024
	global_store_dwordx2 v1, v[238:239], s[10:11] offset:1536
	s_add_u32 s10, s10, 0x400000
	s_addc_u32 s11, s11, 0
	global_load_dwordx4 v[68:71], v0, s[8:9] nt
	global_load_dwordx4 v[72:75], v0, s[8:9] offset:1024 nt
	global_load_dwordx4 v[76:79], v0, s[8:9] offset:2048 nt
	global_load_dwordx4 v[80:83], v0, s[8:9] offset:3072 nt
	s_add_u32 s8, s8, 0x800000
	s_addc_u32 s9, s9, 0
	s_waitcnt vmcnt(32)
	v_pk_mul_f32 v[4:5], v[84:85], v[84:85]
	v_pk_fma_f32 v[4:5], v[86:87], v[86:87], v[4:5]
	v_pk_fma_f32 v[4:5], v[88:89], v[88:89], v[4:5]
	v_pk_fma_f32 v[4:5], v[90:91], v[90:91], v[4:5]
	v_pk_fma_f32 v[4:5], v[92:93], v[92:93], v[4:5]
	v_pk_fma_f32 v[4:5], v[94:95], v[94:95], v[4:5]
	v_pk_fma_f32 v[4:5], v[96:97], v[96:97], v[4:5]
	v_pk_fma_f32 v[4:5], v[98:99], v[98:99], v[4:5]
	v_add_f32_e32 v4, v4, v5
	s_nop 1
	v_add_f32_dpp v4, v4, v4 quad_perm:[1,0,3,2] row_mask:0xf bank_mask:0xf
	s_nop 1
	v_add_f32_dpp v4, v4, v4 quad_perm:[2,3,0,1] row_mask:0xf bank_mask:0xf
	s_nop 1
	v_add_f32_dpp v4, v4, v4 row_half_mirror row_mask:0xf bank_mask:0xf
	s_nop 1
	v_add_f32_dpp v4, v4, v4 row_mirror row_mask:0xf bank_mask:0xf
	s_nop 1
	v_add_f32_dpp v4, v4, v4 row_bcast:15 row_mask:0xa bank_mask:0xf
	s_nop 1
	v_add_f32_dpp v4, v4, v4 row_bcast:31 row_mask:0xc bank_mask:0xf
	s_nop 1
	v_readlane_b32 s20, v4, 63
	s_nop 1
	v_fma_f32 v6, s20, v16, v17
	v_rsq_f32_e32 v6, v6
	s_nop 0
	v_pk_mul_f32 v[84:85], v[84:85], v[6:7] op_sel_hi:[1,0]
	v_pk_mul_f32 v[86:87], v[86:87], v[6:7] op_sel_hi:[1,0]
	v_pk_mul_f32 v[88:89], v[88:89], v[6:7] op_sel_hi:[1,0]
	v_pk_mul_f32 v[90:91], v[90:91], v[6:7] op_sel_hi:[1,0]
	v_pk_mul_f32 v[92:93], v[92:93], v[6:7] op_sel_hi:[1,0]
	v_pk_mul_f32 v[94:95], v[94:95], v[6:7] op_sel_hi:[1,0]
	v_pk_mul_f32 v[96:97], v[96:97], v[6:7] op_sel_hi:[1,0]
	v_pk_mul_f32 v[98:99], v[98:99], v[6:7] op_sel_hi:[1,0]
	v_pk_mul_f32 v[84:85], v[84:85], v[20:21]
	v_pk_mul_f32 v[86:87], v[86:87], v[22:23]
	v_pk_mul_f32 v[88:89], v[88:89], v[24:25]
	v_pk_mul_f32 v[90:91], v[90:91], v[26:27]
	v_pk_mul_f32 v[92:93], v[92:93], v[28:29]
	v_pk_mul_f32 v[94:95], v[94:95], v[30:31]
	v_pk_mul_f32 v[96:97], v[96:97], v[32:33]
	v_pk_mul_f32 v[98:99], v[98:99], v[34:35]
	v_pk_fma_f32 v[84:85], v[84:85], v[52:53], v[36:37]
	v_pk_fma_f32 v[86:87], v[86:87], v[54:55], v[38:39]
	v_pk_fma_f32 v[88:89], v[88:89], v[56:57], v[40:41]
	v_pk_fma_f32 v[90:91], v[90:91], v[58:59], v[42:43]
	v_pk_fma_f32 v[92:93], v[92:93], v[60:61], v[44:45]
	v_pk_fma_f32 v[94:95], v[94:95], v[62:63], v[46:47]
	v_pk_fma_f32 v[96:97], v[96:97], v[64:65], v[48:49]
	v_pk_fma_f32 v[98:99], v[98:99], v[66:67], v[50:51]
	v_cvt_pk_bf16_f32 v240, v84, v85
	v_cvt_pk_bf16_f32 v241, v86, v87
	v_cvt_pk_bf16_f32 v242, v88, v89
	v_cvt_pk_bf16_f32 v243, v90, v91
	v_cvt_pk_bf16_f32 v244, v92, v93
	v_cvt_pk_bf16_f32 v245, v94, v95
	v_cvt_pk_bf16_f32 v246, v96, v97
	v_cvt_pk_bf16_f32 v247, v98, v99
	global_store_dwordx2 v1, v[240:241], s[10:11]
	global_store_dwordx2 v1, v[242:243], s[10:11] offset:512
	global_store_dwordx2 v1, v[244:245], s[10:11] offset:1024
	global_store_dwordx2 v1, v[246:247], s[10:11] offset:1536
	s_add_u32 s10, s10, 0x400000
	s_addc_u32 s11, s11, 0
	global_load_dwordx4 v[84:87], v0, s[8:9] nt
	global_load_dwordx4 v[88:91], v0, s[8:9] offset:1024 nt
	global_load_dwordx4 v[92:95], v0, s[8:9] offset:2048 nt
	global_load_dwordx4 v[96:99], v0, s[8:9] offset:3072 nt
	s_add_u32 s8, s8, 0x800000
	s_addc_u32 s9, s9, 0
	s_waitcnt vmcnt(32)
	v_pk_mul_f32 v[4:5], v[100:101], v[100:101]
	v_pk_fma_f32 v[4:5], v[102:103], v[102:103], v[4:5]
	v_pk_fma_f32 v[4:5], v[104:105], v[104:105], v[4:5]
	v_pk_fma_f32 v[4:5], v[106:107], v[106:107], v[4:5]
	v_pk_fma_f32 v[4:5], v[108:109], v[108:109], v[4:5]
	v_pk_fma_f32 v[4:5], v[110:111], v[110:111], v[4:5]
	v_pk_fma_f32 v[4:5], v[112:113], v[112:113], v[4:5]
	v_pk_fma_f32 v[4:5], v[114:115], v[114:115], v[4:5]
	v_add_f32_e32 v4, v4, v5
	s_nop 1
	v_add_f32_dpp v4, v4, v4 quad_perm:[1,0,3,2] row_mask:0xf bank_mask:0xf
	s_nop 1
	v_add_f32_dpp v4, v4, v4 quad_perm:[2,3,0,1] row_mask:0xf bank_mask:0xf
	s_nop 1
	v_add_f32_dpp v4, v4, v4 row_half_mirror row_mask:0xf bank_mask:0xf
	s_nop 1
	v_add_f32_dpp v4, v4, v4 row_mirror row_mask:0xf bank_mask:0xf
	s_nop 1
	v_add_f32_dpp v4, v4, v4 row_bcast:15 row_mask:0xa bank_mask:0xf
	s_nop 1
	v_add_f32_dpp v4, v4, v4 row_bcast:31 row_mask:0xc bank_mask:0xf
	s_nop 1
	v_readlane_b32 s20, v4, 63
	s_nop 1
	v_fma_f32 v6, s20, v16, v17
	v_rsq_f32_e32 v6, v6
	s_nop 0
	v_pk_mul_f32 v[100:101], v[100:101], v[6:7] op_sel_hi:[1,0]
	v_pk_mul_f32 v[102:103], v[102:103], v[6:7] op_sel_hi:[1,0]
	v_pk_mul_f32 v[104:105], v[104:105], v[6:7] op_sel_hi:[1,0]
	v_pk_mul_f32 v[106:107], v[106:107], v[6:7] op_sel_hi:[1,0]
	v_pk_mul_f32 v[108:109], v[108:109], v[6:7] op_sel_hi:[1,0]
	v_pk_mul_f32 v[110:111], v[110:111], v[6:7] op_sel_hi:[1,0]
	v_pk_mul_f32 v[112:113], v[112:113], v[6:7] op_sel_hi:[1,0]
	v_pk_mul_f32 v[114:115], v[114:115], v[6:7] op_sel_hi:[1,0]
	v_pk_mul_f32 v[100:101], v[100:101], v[20:21]
	v_pk_mul_f32 v[102:103], v[102:103], v[22:23]
	v_pk_mul_f32 v[104:105], v[104:105], v[24:25]
	v_pk_mul_f32 v[106:107], v[106:107], v[26:27]
	v_pk_mul_f32 v[108:109], v[108:109], v[28:29]
	v_pk_mul_f32 v[110:111], v[110:111], v[30:31]
	v_pk_mul_f32 v[112:113], v[112:113], v[32:33]
	v_pk_mul_f32 v[114:115], v[114:115], v[34:35]
	v_pk_fma_f32 v[100:101], v[100:101], v[52:53], v[36:37]
	v_pk_fma_f32 v[102:103], v[102:103], v[54:55], v[38:39]
	v_pk_fma_f32 v[104:105], v[104:105], v[56:57], v[40:41]
	v_pk_fma_f32 v[106:107], v[106:107], v[58:59], v[42:43]
	v_pk_fma_f32 v[108:109], v[108:109], v[60:61], v[44:45]
	v_pk_fma_f32 v[110:111], v[110:111], v[62:63], v[46:47]
	v_pk_fma_f32 v[112:113], v[112:113], v[64:65], v[48:49]
	v_pk_fma_f32 v[114:115], v[114:115], v[66:67], v[50:51]
	v_cvt_pk_bf16_f32 v232, v100, v101
	v_cvt_pk_bf16_f32 v233, v102, v103
	v_cvt_pk_bf16_f32 v234, v104, v105
	v_cvt_pk_bf16_f32 v235, v106, v107
	v_cvt_pk_bf16_f32 v236, v108, v109
	v_cvt_pk_bf16_f32 v237, v110, v111
	v_cvt_pk_bf16_f32 v238, v112, v113
	v_cvt_pk_bf16_f32 v239, v114, v115
	global_store_dwordx2 v1, v[232:233], s[10:11]
	global_store_dwordx2 v1, v[234:235], s[10:11] offset:512
	global_store_dwordx2 v1, v[236:237], s[10:11] offset:1024
	global_store_dwordx2 v1, v[238:239], s[10:11] offset:1536
	s_add_u32 s10, s10, 0x400000
	s_addc_u32 s11, s11, 0
	global_load_dwordx4 v[100:103], v0, s[8:9] nt
	global_load_dwordx4 v[104:107], v0, s[8:9] offset:1024 nt
	global_load_dwordx4 v[108:111], v0, s[8:9] offset:2048 nt
	global_load_dwordx4 v[112:115], v0, s[8:9] offset:3072 nt
	s_add_u32 s8, s8, 0x800000
	s_addc_u32 s9, s9, 0
	s_waitcnt vmcnt(32)
	v_pk_mul_f32 v[4:5], v[116:117], v[116:117]
	v_pk_fma_f32 v[4:5], v[118:119], v[118:119], v[4:5]
	v_pk_fma_f32 v[4:5], v[120:121], v[120:121], v[4:5]
	v_pk_fma_f32 v[4:5], v[122:123], v[122:123], v[4:5]
	v_pk_fma_f32 v[4:5], v[124:125], v[124:125], v[4:5]
	v_pk_fma_f32 v[4:5], v[126:127], v[126:127], v[4:5]
	v_pk_fma_f32 v[4:5], v[128:129], v[128:129], v[4:5]
	v_pk_fma_f32 v[4:5], v[130:131], v[130:131], v[4:5]
	v_add_f32_e32 v4, v4, v5
	s_nop 1
	v_add_f32_dpp v4, v4, v4 quad_perm:[1,0,3,2] row_mask:0xf bank_mask:0xf
	s_nop 1
	v_add_f32_dpp v4, v4, v4 quad_perm:[2,3,0,1] row_mask:0xf bank_mask:0xf
	s_nop 1
	v_add_f32_dpp v4, v4, v4 row_half_mirror row_mask:0xf bank_mask:0xf
	s_nop 1
	v_add_f32_dpp v4, v4, v4 row_mirror row_mask:0xf bank_mask:0xf
	s_nop 1
	v_add_f32_dpp v4, v4, v4 row_bcast:15 row_mask:0xa bank_mask:0xf
	s_nop 1
	v_add_f32_dpp v4, v4, v4 row_bcast:31 row_mask:0xc bank_mask:0xf
	s_nop 1
	v_readlane_b32 s20, v4, 63
	s_nop 1
	v_fma_f32 v6, s20, v16, v17
	v_rsq_f32_e32 v6, v6
	s_nop 0
	v_pk_mul_f32 v[116:117], v[116:117], v[6:7] op_sel_hi:[1,0]
	v_pk_mul_f32 v[118:119], v[118:119], v[6:7] op_sel_hi:[1,0]
	v_pk_mul_f32 v[120:121], v[120:121], v[6:7] op_sel_hi:[1,0]
	v_pk_mul_f32 v[122:123], v[122:123], v[6:7] op_sel_hi:[1,0]
	v_pk_mul_f32 v[124:125], v[124:125], v[6:7] op_sel_hi:[1,0]
	v_pk_mul_f32 v[126:127], v[126:127], v[6:7] op_sel_hi:[1,0]
	v_pk_mul_f32 v[128:129], v[128:129], v[6:7] op_sel_hi:[1,0]
	v_pk_mul_f32 v[130:131], v[130:131], v[6:7] op_sel_hi:[1,0]
	v_pk_mul_f32 v[116:117], v[116:117], v[20:21]
	v_pk_mul_f32 v[118:119], v[118:119], v[22:23]
	v_pk_mul_f32 v[120:121], v[120:121], v[24:25]
	v_pk_mul_f32 v[122:123], v[122:123], v[26:27]
	v_pk_mul_f32 v[124:125], v[124:125], v[28:29]
	v_pk_mul_f32 v[126:127], v[126:127], v[30:31]
	v_pk_mul_f32 v[128:129], v[128:129], v[32:33]
	v_pk_mul_f32 v[130:131], v[130:131], v[34:35]
	v_pk_fma_f32 v[116:117], v[116:117], v[52:53], v[36:37]
	v_pk_fma_f32 v[118:119], v[118:119], v[54:55], v[38:39]
	v_pk_fma_f32 v[120:121], v[120:121], v[56:57], v[40:41]
	v_pk_fma_f32 v[122:123], v[122:123], v[58:59], v[42:43]
	v_pk_fma_f32 v[124:125], v[124:125], v[60:61], v[44:45]
	v_pk_fma_f32 v[126:127], v[126:127], v[62:63], v[46:47]
	v_pk_fma_f32 v[128:129], v[128:129], v[64:65], v[48:49]
	v_pk_fma_f32 v[130:131], v[130:131], v[66:67], v[50:51]
	v_cvt_pk_bf16_f32 v240, v116, v117
	v_cvt_pk_bf16_f32 v241, v118, v119
	v_cvt_pk_bf16_f32 v242, v120, v121
	v_cvt_pk_bf16_f32 v243, v122, v123
	v_cvt_pk_bf16_f32 v244, v124, v125
	v_cvt_pk_bf16_f32 v245, v126, v127
	v_cvt_pk_bf16_f32 v246, v128, v129
	v_cvt_pk_bf16_f32 v247, v130, v131
	global_store_dwordx2 v1, v[240:241], s[10:11]
	global_store_dwordx2 v1, v[242:243], s[10:11] offset:512
	global_store_dwordx2 v1, v[244:245], s[10:11] offset:1024
	global_store_dwordx2 v1, v[246:247], s[10:11] offset:1536
	s_add_u32 s10, s10, 0x400000
	s_addc_u32 s11, s11, 0
	global_load_dwordx4 v[116:119], v0, s[8:9] nt
	global_load_dwordx4 v[120:123], v0, s[8:9] offset:1024 nt
	global_load_dwordx4 v[124:127], v0, s[8:9] offset:2048 nt
	global_load_dwordx4 v[128:131], v0, s[8:9] offset:3072 nt
	s_add_u32 s8, s8, 0x800000
	s_addc_u32 s9, s9, 0
	s_waitcnt vmcnt(24)
	v_pk_add_f32 v[164:165], v[164:165], v[18:19]
	v_pk_add_f32 v[166:167], v[166:167], v[18:19]
	v_pk_add_f32 v[168:169], v[168:169], v[18:19]
	v_pk_add_f32 v[170:171], v[170:171], v[18:19]
	v_pk_add_f32 v[172:173], v[172:173], v[18:19]
	v_pk_add_f32 v[174:175], v[174:175], v[18:19]
	v_pk_add_f32 v[176:177], v[176:177], v[18:19]
	v_pk_add_f32 v[178:179], v[178:179], v[18:19]
	s_add_u32 s14, s12, 0x18000
	s_addc_u32 s15, s13, 0
	s_add_u32 s16, s14, 0x1000
	s_addc_u32 s17, s15, 0
	global_load_dwordx4 v[36:39], v0, s[14:15]
	global_load_dwordx4 v[40:43], v0, s[14:15] offset:1024
	global_load_dwordx4 v[44:47], v0, s[14:15] offset:2048
	global_load_dwordx4 v[48:51], v0, s[14:15] offset:3072
	global_load_dwordx4 v[52:55], v0, s[16:17]
	global_load_dwordx4 v[56:59], v0, s[16:17] offset:1024
	global_load_dwordx4 v[60:63], v0, s[16:17] offset:2048
	global_load_dwordx4 v[64:67], v0, s[16:17] offset:3072
	v_pk_mul_f32 v[4:5], v[68:69], v[68:69]
	v_pk_fma_f32 v[4:5], v[70:71], v[70:71], v[4:5]
	v_pk_fma_f32 v[4:5], v[72:73], v[72:73], v[4:5]
	v_pk_fma_f32 v[4:5], v[74:75], v[74:75], v[4:5]
	v_pk_fma_f32 v[4:5], v[76:77], v[76:77], v[4:5]
	v_pk_fma_f32 v[4:5], v[78:79], v[78:79], v[4:5]
	v_pk_fma_f32 v[4:5], v[80:81], v[80:81], v[4:5]
	v_pk_fma_f32 v[4:5], v[82:83], v[82:83], v[4:5]
	v_add_f32_e32 v4, v4, v5
	s_nop 1
	v_add_f32_dpp v4, v4, v4 quad_perm:[1,0,3,2] row_mask:0xf bank_mask:0xf
	s_nop 1
	v_add_f32_dpp v4, v4, v4 quad_perm:[2,3,0,1] row_mask:0xf bank_mask:0xf
	s_nop 1
	v_add_f32_dpp v4, v4, v4 row_half_mirror row_mask:0xf bank_mask:0xf
	s_nop 1
	v_add_f32_dpp v4, v4, v4 row_mirror row_mask:0xf bank_mask:0xf
	s_nop 1
	v_add_f32_dpp v4, v4, v4 row_bcast:15 row_mask:0xa bank_mask:0xf
	s_nop 1
	v_add_f32_dpp v4, v4, v4 row_bcast:31 row_mask:0xc bank_mask:0xf
	s_nop 1
	v_readlane_b32 s20, v4, 63
	s_nop 1
	v_fma_f32 v6, s20, v16, v17
	v_rsq_f32_e32 v6, v6
	s_nop 0
	v_pk_mul_f32 v[68:69], v[68:69], v[6:7] op_sel_hi:[1,0]
	v_pk_mul_f32 v[70:71], v[70:71], v[6:7] op_sel_hi:[1,0]
	v_pk_mul_f32 v[72:73], v[72:73], v[6:7] op_sel_hi:[1,0]
	v_pk_mul_f32 v[74:75], v[74:75], v[6:7] op_sel_hi:[1,0]
	v_pk_mul_f32 v[76:77], v[76:77], v[6:7] op_sel_hi:[1,0]
	v_pk_mul_f32 v[78:79], v[78:79], v[6:7] op_sel_hi:[1,0]
	v_pk_mul_f32 v[80:81], v[80:81], v[6:7] op_sel_hi:[1,0]
	v_pk_mul_f32 v[82:83], v[82:83], v[6:7] op_sel_hi:[1,0]
	v_pk_mul_f32 v[68:69], v[68:69], v[20:21]
	v_pk_mul_f32 v[70:71], v[70:71], v[22:23]
	v_pk_mul_f32 v[72:73], v[72:73], v[24:25]
	v_pk_mul_f32 v[74:75], v[74:75], v[26:27]
	v_pk_mul_f32 v[76:77], v[76:77], v[28:29]
	v_pk_mul_f32 v[78:79], v[78:79], v[30:31]
	v_pk_mul_f32 v[80:81], v[80:81], v[32:33]
	v_pk_mul_f32 v[82:83], v[82:83], v[34:35]
	v_pk_fma_f32 v[68:69], v[68:69], v[164:165], v[148:149]
	v_pk_fma_f32 v[70:71], v[70:71], v[166:167], v[150:151]
	v_pk_fma_f32 v[72:73], v[72:73], v[168:169], v[152:153]
	v_pk_fma_f32 v[74:75], v[74:75], v[170:171], v[154:155]
	v_pk_fma_f32 v[76:77], v[76:77], v[172:173], v[156:157]
	v_pk_fma_f32 v[78:79], v[78:79], v[174:175], v[158:159]
	v_pk_fma_f32 v[80:81], v[80:81], v[176:177], v[160:161]
	v_pk_fma_f32 v[82:83], v[82:83], v[178:179], v[162:163]
	v_cvt_pk_bf16_f32 v232, v68, v69
	v_cvt_pk_bf16_f32 v233, v70, v71
	v_cvt_pk_bf16_f32 v234, v72, v73
	v_cvt_pk_bf16_f32 v235, v74, v75
	v_cvt_pk_bf16_f32 v236, v76, v77
	v_cvt_pk_bf16_f32 v237, v78, v79
	v_cvt_pk_bf16_f32 v238, v80, v81
	v_cvt_pk_bf16_f32 v239, v82, v83
	global_store_dwordx2 v1, v[232:233], s[10:11]
	global_store_dwordx2 v1, v[234:235], s[10:11] offset:512
	global_store_dwordx2 v1, v[236:237], s[10:11] offset:1024
	global_store_dwordx2 v1, v[238:239], s[10:11] offset:1536
	s_add_u32 s10, s10, 0x400000
	s_addc_u32 s11, s11, 0
	s_waitcnt vmcnt(28)
	v_pk_mul_f32 v[4:5], v[84:85], v[84:85]
	v_pk_fma_f32 v[4:5], v[86:87], v[86:87], v[4:5]
	v_pk_fma_f32 v[4:5], v[88:89], v[88:89], v[4:5]
	v_pk_fma_f32 v[4:5], v[90:91], v[90:91], v[4:5]
	v_pk_fma_f32 v[4:5], v[92:93], v[92:93], v[4:5]
	v_pk_fma_f32 v[4:5], v[94:95], v[94:95], v[4:5]
	v_pk_fma_f32 v[4:5], v[96:97], v[96:97], v[4:5]
	v_pk_fma_f32 v[4:5], v[98:99], v[98:99], v[4:5]
	v_add_f32_e32 v4, v4, v5
	s_nop 1
	v_add_f32_dpp v4, v4, v4 quad_perm:[1,0,3,2] row_mask:0xf bank_mask:0xf
	s_nop 1
	v_add_f32_dpp v4, v4, v4 quad_perm:[2,3,0,1] row_mask:0xf bank_mask:0xf
	s_nop 1
	v_add_f32_dpp v4, v4, v4 row_half_mirror row_mask:0xf bank_mask:0xf
	s_nop 1
	v_add_f32_dpp v4, v4, v4 row_mirror row_mask:0xf bank_mask:0xf
	s_nop 1
	v_add_f32_dpp v4, v4, v4 row_bcast:15 row_mask:0xa bank_mask:0xf
	s_nop 1
	v_add_f32_dpp v4, v4, v4 row_bcast:31 row_mask:0xc bank_mask:0xf
	s_nop 1
	v_readlane_b32 s20, v4, 63
	s_nop 1
	v_fma_f32 v6, s20, v16, v17
	v_rsq_f32_e32 v6, v6
	s_nop 0
	v_pk_mul_f32 v[84:85], v[84:85], v[6:7] op_sel_hi:[1,0]
	v_pk_mul_f32 v[86:87], v[86:87], v[6:7] op_sel_hi:[1,0]
	v_pk_mul_f32 v[88:89], v[88:89], v[6:7] op_sel_hi:[1,0]
	v_pk_mul_f32 v[90:91], v[90:91], v[6:7] op_sel_hi:[1,0]
	v_pk_mul_f32 v[92:93], v[92:93], v[6:7] op_sel_hi:[1,0]
	v_pk_mul_f32 v[94:95], v[94:95], v[6:7] op_sel_hi:[1,0]
	v_pk_mul_f32 v[96:97], v[96:97], v[6:7] op_sel_hi:[1,0]
	v_pk_mul_f32 v[98:99], v[98:99], v[6:7] op_sel_hi:[1,0]
	v_pk_mul_f32 v[84:85], v[84:85], v[20:21]
	v_pk_mul_f32 v[86:87], v[86:87], v[22:23]
	v_pk_mul_f32 v[88:89], v[88:89], v[24:25]
	v_pk_mul_f32 v[90:91], v[90:91], v[26:27]
	v_pk_mul_f32 v[92:93], v[92:93], v[28:29]
	v_pk_mul_f32 v[94:95], v[94:95], v[30:31]
	v_pk_mul_f32 v[96:97], v[96:97], v[32:33]
	v_pk_mul_f32 v[98:99], v[98:99], v[34:35]
	v_pk_fma_f32 v[84:85], v[84:85], v[164:165], v[148:149]
	v_pk_fma_f32 v[86:87], v[86:87], v[166:167], v[150:151]
	v_pk_fma_f32 v[88:89], v[88:89], v[168:169], v[152:153]
	v_pk_fma_f32 v[90:91], v[90:91], v[170:171], v[154:155]
	v_pk_fma_f32 v[92:93], v[92:93], v[172:173], v[156:157]
	v_pk_fma_f32 v[94:95], v[94:95], v[174:175], v[158:159]
	v_pk_fma_f32 v[96:97], v[96:97], v[176:177], v[160:161]
	v_pk_fma_f32 v[98:99], v[98:99], v[178:179], v[162:163]
	v_cvt_pk_bf16_f32 v240, v84, v85
	v_cvt_pk_bf16_f32 v241, v86, v87
	v_cvt_pk_bf16_f32 v242, v88, v89
	v_cvt_pk_bf16_f32 v243, v90, v91
	v_cvt_pk_bf16_f32 v244, v92, v93
	v_cvt_pk_bf16_f32 v245, v94, v95
	v_cvt_pk_bf16_f32 v246, v96, v97
	v_cvt_pk_bf16_f32 v247, v98, v99
	global_store_dwordx2 v1, v[240:241], s[10:11]
	global_store_dwordx2 v1, v[242:243], s[10:11] offset:512
	global_store_dwordx2 v1, v[244:245], s[10:11] offset:1024
	global_store_dwordx2 v1, v[246:247], s[10:11] offset:1536
	s_add_u32 s10, s10, 0x400000
	s_addc_u32 s11, s11, 0
	s_waitcnt vmcnt(24)
	v_pk_mul_f32 v[4:5], v[100:101], v[100:101]
	v_pk_fma_f32 v[4:5], v[102:103], v[102:103], v[4:5]
	v_pk_fma_f32 v[4:5], v[104:105], v[104:105], v[4:5]
	v_pk_fma_f32 v[4:5], v[106:107], v[106:107], v[4:5]
	v_pk_fma_f32 v[4:5], v[108:109], v[108:109], v[4:5]
	v_pk_fma_f32 v[4:5], v[110:111], v[110:111], v[4:5]
	v_pk_fma_f32 v[4:5], v[112:113], v[112:113], v[4:5]
	v_pk_fma_f32 v[4:5], v[114:115], v[114:115], v[4:5]
	v_add_f32_e32 v4, v4, v5
	s_nop 1
	v_add_f32_dpp v4, v4, v4 quad_perm:[1,0,3,2] row_mask:0xf bank_mask:0xf
	s_nop 1
	v_add_f32_dpp v4, v4, v4 quad_perm:[2,3,0,1] row_mask:0xf bank_mask:0xf
	s_nop 1
	v_add_f32_dpp v4, v4, v4 row_half_mirror row_mask:0xf bank_mask:0xf
	s_nop 1
	v_add_f32_dpp v4, v4, v4 row_mirror row_mask:0xf bank_mask:0xf
	s_nop 1
	v_add_f32_dpp v4, v4, v4 row_bcast:15 row_mask:0xa bank_mask:0xf
	s_nop 1
	v_add_f32_dpp v4, v4, v4 row_bcast:31 row_mask:0xc bank_mask:0xf
	s_nop 1
	v_readlane_b32 s20, v4, 63
	s_nop 1
	v_fma_f32 v6, s20, v16, v17
	v_rsq_f32_e32 v6, v6
	s_nop 0
	v_pk_mul_f32 v[100:101], v[100:101], v[6:7] op_sel_hi:[1,0]
	v_pk_mul_f32 v[102:103], v[102:103], v[6:7] op_sel_hi:[1,0]
	v_pk_mul_f32 v[104:105], v[104:105], v[6:7] op_sel_hi:[1,0]
	v_pk_mul_f32 v[106:107], v[106:107], v[6:7] op_sel_hi:[1,0]
	v_pk_mul_f32 v[108:109], v[108:109], v[6:7] op_sel_hi:[1,0]
	v_pk_mul_f32 v[110:111], v[110:111], v[6:7] op_sel_hi:[1,0]
	v_pk_mul_f32 v[112:113], v[112:113], v[6:7] op_sel_hi:[1,0]
	v_pk_mul_f32 v[114:115], v[114:115], v[6:7] op_sel_hi:[1,0]
	v_pk_mul_f32 v[100:101], v[100:101], v[20:21]
	v_pk_mul_f32 v[102:103], v[102:103], v[22:23]
	v_pk_mul_f32 v[104:105], v[104:105], v[24:25]
	v_pk_mul_f32 v[106:107], v[106:107], v[26:27]
	v_pk_mul_f32 v[108:109], v[108:109], v[28:29]
	v_pk_mul_f32 v[110:111], v[110:111], v[30:31]
	v_pk_mul_f32 v[112:113], v[112:113], v[32:33]
	v_pk_mul_f32 v[114:115], v[114:115], v[34:35]
	v_pk_fma_f32 v[100:101], v[100:101], v[164:165], v[148:149]
	v_pk_fma_f32 v[102:103], v[102:103], v[166:167], v[150:151]
	v_pk_fma_f32 v[104:105], v[104:105], v[168:169], v[152:153]
	v_pk_fma_f32 v[106:107], v[106:107], v[170:171], v[154:155]
	v_pk_fma_f32 v[108:109], v[108:109], v[172:173], v[156:157]
	v_pk_fma_f32 v[110:111], v[110:111], v[174:175], v[158:159]
	v_pk_fma_f32 v[112:113], v[112:113], v[176:177], v[160:161]
	v_pk_fma_f32 v[114:115], v[114:115], v[178:179], v[162:163]
	v_cvt_pk_bf16_f32 v232, v100, v101
	v_cvt_pk_bf16_f32 v233, v102, v103
	v_cvt_pk_bf16_f32 v234, v104, v105
	v_cvt_pk_bf16_f32 v235, v106, v107
	v_cvt_pk_bf16_f32 v236, v108, v109
	v_cvt_pk_bf16_f32 v237, v110, v111
	v_cvt_pk_bf16_f32 v238, v112, v113
	v_cvt_pk_bf16_f32 v239, v114, v115
	global_store_dwordx2 v1, v[232:233], s[10:11]
	global_store_dwordx2 v1, v[234:235], s[10:11] offset:512
	global_store_dwordx2 v1, v[236:237], s[10:11] offset:1024
	global_store_dwordx2 v1, v[238:239], s[10:11] offset:1536
	s_add_u32 s10, s10, 0x400000
	s_addc_u32 s11, s11, 0
	s_waitcnt vmcnt(20)
	v_pk_mul_f32 v[4:5], v[116:117], v[116:117]
	v_pk_fma_f32 v[4:5], v[118:119], v[118:119], v[4:5]
	v_pk_fma_f32 v[4:5], v[120:121], v[120:121], v[4:5]
	v_pk_fma_f32 v[4:5], v[122:123], v[122:123], v[4:5]
	v_pk_fma_f32 v[4:5], v[124:125], v[124:125], v[4:5]
	v_pk_fma_f32 v[4:5], v[126:127], v[126:127], v[4:5]
	v_pk_fma_f32 v[4:5], v[128:129], v[128:129], v[4:5]
	v_pk_fma_f32 v[4:5], v[130:131], v[130:131], v[4:5]
	v_add_f32_e32 v4, v4, v5
	s_nop 1
	v_add_f32_dpp v4, v4, v4 quad_perm:[1,0,3,2] row_mask:0xf bank_mask:0xf
	s_nop 1
	v_add_f32_dpp v4, v4, v4 quad_perm:[2,3,0,1] row_mask:0xf bank_mask:0xf
	s_nop 1
	v_add_f32_dpp v4, v4, v4 row_half_mirror row_mask:0xf bank_mask:0xf
	s_nop 1
	v_add_f32_dpp v4, v4, v4 row_mirror row_mask:0xf bank_mask:0xf
	s_nop 1
	v_add_f32_dpp v4, v4, v4 row_bcast:15 row_mask:0xa bank_mask:0xf
	s_nop 1
	v_add_f32_dpp v4, v4, v4 row_bcast:31 row_mask:0xc bank_mask:0xf
	s_nop 1
	v_readlane_b32 s20, v4, 63
	s_nop 1
	v_fma_f32 v6, s20, v16, v17
	v_rsq_f32_e32 v6, v6
	s_nop 0
	v_pk_mul_f32 v[116:117], v[116:117], v[6:7] op_sel_hi:[1,0]
	v_pk_mul_f32 v[118:119], v[118:119], v[6:7] op_sel_hi:[1,0]
	v_pk_mul_f32 v[120:121], v[120:121], v[6:7] op_sel_hi:[1,0]
	v_pk_mul_f32 v[122:123], v[122:123], v[6:7] op_sel_hi:[1,0]
	v_pk_mul_f32 v[124:125], v[124:125], v[6:7] op_sel_hi:[1,0]
	v_pk_mul_f32 v[126:127], v[126:127], v[6:7] op_sel_hi:[1,0]
	v_pk_mul_f32 v[128:129], v[128:129], v[6:7] op_sel_hi:[1,0]
	v_pk_mul_f32 v[130:131], v[130:131], v[6:7] op_sel_hi:[1,0]
	v_pk_mul_f32 v[116:117], v[116:117], v[20:21]
	v_pk_mul_f32 v[118:119], v[118:119], v[22:23]
	v_pk_mul_f32 v[120:121], v[120:121], v[24:25]
	v_pk_mul_f32 v[122:123], v[122:123], v[26:27]
	v_pk_mul_f32 v[124:125], v[124:125], v[28:29]
	v_pk_mul_f32 v[126:127], v[126:127], v[30:31]
	v_pk_mul_f32 v[128:129], v[128:129], v[32:33]
	v_pk_mul_f32 v[130:131], v[130:131], v[34:35]
	v_pk_fma_f32 v[116:117], v[116:117], v[164:165], v[148:149]
	v_pk_fma_f32 v[118:119], v[118:119], v[166:167], v[150:151]
	v_pk_fma_f32 v[120:121], v[120:121], v[168:169], v[152:153]
	v_pk_fma_f32 v[122:123], v[122:123], v[170:171], v[154:155]
	v_pk_fma_f32 v[124:125], v[124:125], v[172:173], v[156:157]
	v_pk_fma_f32 v[126:127], v[126:127], v[174:175], v[158:159]
	v_pk_fma_f32 v[128:129], v[128:129], v[176:177], v[160:161]
	v_pk_fma_f32 v[130:131], v[130:131], v[178:179], v[162:163]
	v_cvt_pk_bf16_f32 v240, v116, v117
	v_cvt_pk_bf16_f32 v241, v118, v119
	v_cvt_pk_bf16_f32 v242, v120, v121
	v_cvt_pk_bf16_f32 v243, v122, v123
	v_cvt_pk_bf16_f32 v244, v124, v125
	v_cvt_pk_bf16_f32 v245, v126, v127
	v_cvt_pk_bf16_f32 v246, v128, v129
	v_cvt_pk_bf16_f32 v247, v130, v131
	global_store_dwordx2 v1, v[240:241], s[10:11]
	global_store_dwordx2 v1, v[242:243], s[10:11] offset:512
	global_store_dwordx2 v1, v[244:245], s[10:11] offset:1024
	global_store_dwordx2 v1, v[246:247], s[10:11] offset:1536
	s_add_u32 s10, s10, 0x400000
	s_addc_u32 s11, s11, 0
	s_cmpk_lt_u32 s6, 0x400
	s_cbranch_scc0 .Lp1_done
	s_waitcnt vmcnt(16)
	v_pk_add_f32 v[52:53], v[52:53], v[18:19]
	v_pk_add_f32 v[54:55], v[54:55], v[18:19]
	v_pk_add_f32 v[56:57], v[56:57], v[18:19]
	v_pk_add_f32 v[58:59], v[58:59], v[18:19]
	v_pk_add_f32 v[60:61], v[60:61], v[18:19]
	v_pk_add_f32 v[62:63], v[62:63], v[18:19]
	v_pk_add_f32 v[64:65], v[64:65], v[18:19]
	v_pk_add_f32 v[66:67], v[66:67], v[18:19]
	s_lshl_b32 s10, s6, 11
	s_add_u32 s10, s10, 0x5e85000
	s_addc_u32 s11, 0, 0
	s_add_u32 s10, s74, s10
	s_addc_u32 s11, s75, s11
	v_pk_mul_f32 v[4:5], v[132:133], v[132:133]
	v_pk_fma_f32 v[4:5], v[134:135], v[134:135], v[4:5]
	v_pk_fma_f32 v[4:5], v[136:137], v[136:137], v[4:5]
	v_pk_fma_f32 v[4:5], v[138:139], v[138:139], v[4:5]
	v_pk_fma_f32 v[4:5], v[140:141], v[140:141], v[4:5]
	v_pk_fma_f32 v[4:5], v[142:143], v[142:143], v[4:5]
	v_pk_fma_f32 v[4:5], v[144:145], v[144:145], v[4:5]
	v_pk_fma_f32 v[4:5], v[146:147], v[146:147], v[4:5]
	v_add_f32_e32 v4, v4, v5
	s_nop 1
	v_add_f32_dpp v4, v4, v4 quad_perm:[1,0,3,2] row_mask:0xf bank_mask:0xf
	s_nop 1
	v_add_f32_dpp v4, v4, v4 quad_perm:[2,3,0,1] row_mask:0xf bank_mask:0xf
	s_nop 1
	v_add_f32_dpp v4, v4, v4 row_half_mirror row_mask:0xf bank_mask:0xf
	s_nop 1
	v_add_f32_dpp v4, v4, v4 row_mirror row_mask:0xf bank_mask:0xf
	s_nop 1
	v_add_f32_dpp v4, v4, v4 row_bcast:15 row_mask:0xa bank_mask:0xf
	s_nop 1
	v_add_f32_dpp v4, v4, v4 row_bcast:31 row_mask:0xc bank_mask:0xf
	s_nop 1
	v_readlane_b32 s20, v4, 63
	s_nop 1
	v_fma_f32 v6, s20, v16, v17
	v_rsq_f32_e32 v6, v6
	s_nop 0
	v_pk_mul_f32 v[132:133], v[132:133], v[6:7] op_sel_hi:[1,0]
	v_pk_mul_f32 v[134:135], v[134:135], v[6:7] op_sel_hi:[1,0]
	v_pk_mul_f32 v[136:137], v[136:137], v[6:7] op_sel_hi:[1,0]
	v_pk_mul_f32 v[138:139], v[138:139], v[6:7] op_sel_hi:[1,0]
	v_pk_mul_f32 v[140:141], v[140:141], v[6:7] op_sel_hi:[1,0]
	v_pk_mul_f32 v[142:143], v[142:143], v[6:7] op_sel_hi:[1,0]
	v_pk_mul_f32 v[144:145], v[144:145], v[6:7] op_sel_hi:[1,0]
	v_pk_mul_f32 v[146:147], v[146:147], v[6:7] op_sel_hi:[1,0]
	v_pk_mul_f32 v[132:133], v[132:133], v[20:21]
	v_pk_mul_f32 v[134:135], v[134:135], v[22:23]
	v_pk_mul_f32 v[136:137], v[136:137], v[24:25]
	v_pk_mul_f32 v[138:139], v[138:139], v[26:27]
	v_pk_mul_f32 v[140:141], v[140:141], v[28:29]
	v_pk_mul_f32 v[142:143], v[142:143], v[30:31]
	v_pk_mul_f32 v[144:145], v[144:145], v[32:33]
	v_pk_mul_f32 v[146:147], v[146:147], v[34:35]
	v_pk_fma_f32 v[132:133], v[132:133], v[52:53], v[36:37]
	v_pk_fma_f32 v[134:135], v[134:135], v[54:55], v[38:39]
	v_pk_fma_f32 v[136:137], v[136:137], v[56:57], v[40:41]
	v_pk_fma_f32 v[138:139], v[138:139], v[58:59], v[42:43]
	v_pk_fma_f32 v[140:141], v[140:141], v[60:61], v[44:45]
	v_pk_fma_f32 v[142:143], v[142:143], v[62:63], v[46:47]
	v_pk_fma_f32 v[144:145], v[144:145], v[64:65], v[48:49]
	v_pk_fma_f32 v[146:147], v[146:147], v[66:67], v[50:51]
	v_cvt_pk_bf16_f32 v232, v132, v133
	v_cvt_pk_bf16_f32 v233, v134, v135
	v_cvt_pk_bf16_f32 v234, v136, v137
	v_cvt_pk_bf16_f32 v235, v138, v139
	v_cvt_pk_bf16_f32 v236, v140, v141
	v_cvt_pk_bf16_f32 v237, v142, v143
	v_cvt_pk_bf16_f32 v238, v144, v145
	v_cvt_pk_bf16_f32 v239, v146, v147
	global_store_dwordx2 v1, v[232:233], s[10:11]
	global_store_dwordx2 v1, v[234:235], s[10:11] offset:512
	global_store_dwordx2 v1, v[236:237], s[10:11] offset:1024
	global_store_dwordx2 v1, v[238:239], s[10:11] offset:1536
